# v60 + P6 cross-attention MFMA blocks: LDS fragment reads software-pipelined 3-4 ahead (register pool), waits recomputed
# baseline (speedup 1.0000x reference)
; __device__ __forceinline__ int crow(int r,int hi){return (r&3)+8*(r>>2)+4*hi;}
; #define XLAS __attribute__((address_space(3)))
; __device__ __forceinline__ int crow(int r, int hi) { return (r & 3) + 8 * (r >> 2) + 4 * hi; }
; #define X_LOADV(c)  do { _Pragma("unroll") for (int i_ = 0; i_ < 4; ++i_) st[i_] = *(const u32x4*)(Vg + (size_t)(c) * 64 * 2048 + i_ * 64); } while (0)
; __device__ __forceinline__ void unit(int b, int h, int qblk, const bf16_t* __restrict__ CQ, const bf16_t* __restrict__ CK, const bf16_t* __restrict__ CVT, bf16_t* __restrict__ CO, XLAS unsigned char* lds, const int wv) {
;     ...
;     XLAS float* wsf = (XLAS float*)(lds + X_WSF) + wid * 64;
;     if (hi == 0) wsf[r32] = l;
;     asm volatile("s_waitcnt lgkmcnt(0)" ::: "memory");
;     float rli[16];
; #pragma unroll
;     for (int r = 0; r < 16; ++r) rli[r] = __builtin_amdgcn_rcpf(wsf[crow(r, hi)]);
;     ...
;     for (int c = 0; c < 4; ++c) {
;         const int buf = (c & 1) ? XB1 : XB0, nbuf = (c & 1) ? XB0 : XB1;
;         if (c < 3) X_LOADV(c + 1);
;         f32x16 o[2]; o[0] = f32x16{}; o[1] = f32x16{};
; #pragma unroll
;         for (int j = 0; j < 16; ++j)
; #pragma unroll
;             for (int dt = 0; dt < 2; ++dt) {
;                 const bf16x8 vf = *(const XLAS bf16x8*)(lds + buf + voff + dt * 512 + j * 2048);
;                 o[dt] = __builtin_amdgcn_mfma_f32_32x32x16_bf16(__builtin_bit_cast(bf16x8, pw[j]), vf, o[dt], 0, 0, 0);
;             }
.LBB0_1144:
	s_or_b64 exec, exec, s[14:15]
	s_mov_b32 s30, s23
	s_mov_b32 s31, 0
	v_lshl_add_u64 v[242:243], v[144:145], 0, s[30:31]
	global_load_dwordx4 v[226:229], v[242:243], off
	global_load_dwordx4 v[230:233], v[242:243], off offset:128
	global_load_dwordx4 v[234:237], v[242:243], off offset:256
	global_load_dwordx4 v[238:241], v[242:243], off offset:384
	v_lshlrev_b32_e32 v0, 4, v191
	s_waitcnt lgkmcnt(0)
	v_lshlrev_b32_e32 v1, 10, v192
	s_waitcnt lgkmcnt(0)
	v_add3_u32 v104, 0, v1, v0
	ds_read_b128 v[96:99], v104
	ds_read_b128 v[244:247], v104 offset:512
	ds_read_b128 v[248:251], v104 offset:2048
	ds_read_b128 v[148:151], v104 offset:2560
	ds_read_b128 v[152:155], v104 offset:4096
	s_waitcnt lgkmcnt(4)
	v_mfma_f32_32x32x16_bf16 v[16:31], v[92:95], v[96:99], 0
	v_lshl_add_u32 v105, v192, 4, s17
	s_add_i32 s4, s4, 0x10800
	s_lshl_b64 s[12:13], s[12:13], 11
	s_add_u32 s12, s18, s12
	s_addc_u32 s13, s19, s13
	s_lshl_b32 s14, s16, 1
	s_add_u32 s12, s12, s14
	ds_read_b128 v[156:159], v104 offset:4608
	s_waitcnt lgkmcnt(4)
	v_mfma_f32_32x32x16_bf16 v[0:15], v[92:95], v[244:247], 0
	s_addc_u32 s13, s13, 0
	s_add_i32 s2, s2, 1
	s_addk_i32 s21, 0x100
	s_cmp_lt_i32 s2, s3
	ds_read_b128 v[96:99], v104 offset:6144
	s_waitcnt lgkmcnt(4)
	v_mfma_f32_32x32x16_bf16 v[16:31], v[88:91], v[248:251], v[16:31]
	ds_read_b128 v[244:247], v104 offset:6656
	s_waitcnt lgkmcnt(4)
	v_mfma_f32_32x32x16_bf16 v[0:15], v[88:91], v[148:151], v[0:15]
	ds_read_b128 v[248:251], v104 offset:8192
	s_waitcnt lgkmcnt(4)
	v_mfma_f32_32x32x16_bf16 v[16:31], v[84:87], v[152:155], v[16:31]
	ds_read_b128 v[148:151], v104 offset:8704
	s_waitcnt lgkmcnt(4)
	v_mfma_f32_32x32x16_bf16 v[0:15], v[84:87], v[156:159], v[0:15]
	ds_read_b128 v[152:155], v104 offset:10240
	s_waitcnt lgkmcnt(4)
	v_mfma_f32_32x32x16_bf16 v[16:31], v[80:83], v[96:99], v[16:31]
	ds_read_b128 v[156:159], v104 offset:10752
	s_waitcnt lgkmcnt(4)
	v_mfma_f32_32x32x16_bf16 v[0:15], v[80:83], v[244:247], v[0:15]
	ds_read_b128 v[96:99], v104 offset:12288
	s_waitcnt lgkmcnt(4)
	v_mfma_f32_32x32x16_bf16 v[16:31], v[76:79], v[248:251], v[16:31]
	ds_read_b128 v[244:247], v104 offset:12800
	s_waitcnt lgkmcnt(4)
	v_mfma_f32_32x32x16_bf16 v[0:15], v[76:79], v[148:151], v[0:15]
	ds_read_b128 v[248:251], v104 offset:14336
	s_waitcnt lgkmcnt(4)
	v_mfma_f32_32x32x16_bf16 v[16:31], v[72:75], v[152:155], v[16:31]
	ds_read_b128 v[148:151], v104 offset:14848
	s_waitcnt lgkmcnt(4)
	v_mfma_f32_32x32x16_bf16 v[0:15], v[72:75], v[156:159], v[0:15]
	ds_read_b128 v[152:155], v104 offset:16384
	s_waitcnt lgkmcnt(4)
	v_mfma_f32_32x32x16_bf16 v[16:31], v[68:71], v[96:99], v[16:31]
	ds_read_b128 v[156:159], v104 offset:16896
	s_waitcnt lgkmcnt(4)
	v_mfma_f32_32x32x16_bf16 v[0:15], v[68:71], v[244:247], v[0:15]
	ds_read_b128 v[96:99], v104 offset:18432
	s_waitcnt lgkmcnt(4)
	v_mfma_f32_32x32x16_bf16 v[16:31], v[64:67], v[248:251], v[16:31]
	ds_read_b128 v[244:247], v104 offset:18944
	s_waitcnt lgkmcnt(4)
	v_mfma_f32_32x32x16_bf16 v[0:15], v[64:67], v[148:151], v[0:15]
	ds_read_b128 v[248:251], v104 offset:20480
	s_waitcnt lgkmcnt(4)
	v_mfma_f32_32x32x16_bf16 v[16:31], v[60:63], v[152:155], v[16:31]
	ds_read_b128 v[148:151], v104 offset:20992
	s_waitcnt lgkmcnt(4)
	v_mfma_f32_32x32x16_bf16 v[0:15], v[60:63], v[156:159], v[0:15]
	ds_read_b128 v[152:155], v104 offset:22528
	s_waitcnt lgkmcnt(4)
	v_mfma_f32_32x32x16_bf16 v[16:31], v[56:59], v[96:99], v[16:31]
	ds_read_b128 v[156:159], v104 offset:23040
	s_waitcnt lgkmcnt(4)
	v_mfma_f32_32x32x16_bf16 v[0:15], v[56:59], v[244:247], v[0:15]
	ds_read_b128 v[96:99], v104 offset:24576
	s_waitcnt lgkmcnt(4)
	v_mfma_f32_32x32x16_bf16 v[16:31], v[52:55], v[248:251], v[16:31]
	s_waitcnt lgkmcnt(3)
	v_mfma_f32_32x32x16_bf16 v[0:15], v[52:55], v[148:151], v[0:15]
	s_waitcnt lgkmcnt(2)
	v_mfma_f32_32x32x16_bf16 v[16:31], v[48:51], v[152:155], v[16:31]
	s_waitcnt lgkmcnt(1)
	v_mfma_f32_32x32x16_bf16 v[0:15], v[48:51], v[156:159], v[0:15]
	ds_read_b128 v[100:103], v104 offset:25088
	s_waitcnt lgkmcnt(1)
	v_mfma_f32_32x32x16_bf16 v[16:31], v[44:47], v[96:99], v[16:31]
	ds_read_b128 v[96:99], v105
	ds_read_b128 v[106:109], v105 offset:32
	ds_read_b128 v[122:125], v104 offset:27136
	s_waitcnt lgkmcnt(2)
	v_rcp_f32_e32 v121, v96
	v_rcp_f32_e32 v120, v97
	v_rcp_f32_e32 v119, v98
	v_mfma_f32_32x32x16_bf16 v[0:15], v[44:47], v[100:103], v[0:15]
	v_rcp_f32_e32 v118, v99
	ds_read_b128 v[96:99], v104 offset:26624
	ds_read_b128 v[100:103], v105 offset:64
	s_waitcnt lgkmcnt(3)
	v_rcp_f32_e32 v117, v106
	v_rcp_f32_e32 v116, v107
	v_rcp_f32_e32 v115, v108
	v_rcp_f32_e32 v113, v109
	s_waitcnt lgkmcnt(1)
	v_mfma_f32_32x32x16_bf16 v[16:31], v[40:43], v[96:99], v[16:31]
	ds_read_b128 v[96:99], v105 offset:96
	s_waitcnt lgkmcnt(1)
	v_rcp_f32_e32 v114, v100
	v_rcp_f32_e32 v112, v101
	v_rcp_f32_e32 v111, v102
	v_rcp_f32_e32 v110, v103
	s_waitcnt lgkmcnt(0)
	v_rcp_f32_e32 v108, v96
	v_rcp_f32_e32 v107, v97
	v_mfma_f32_32x32x16_bf16 v[0:15], v[40:43], v[122:125], v[0:15]
	v_rcp_f32_e32 v106, v98
	v_rcp_f32_e32 v105, v99
	ds_read_b128 v[96:99], v104 offset:28672
	ds_read_b128 v[100:103], v104 offset:29184
	v_lshrrev_b32_e32 v125, 3, v190
	s_waitcnt lgkmcnt(1)
	v_mfma_f32_32x32x16_bf16 v[16:31], v[36:39], v[96:99], v[16:31]
	v_lshlrev_b32_e32 v96, 9, v192
	v_lshlrev_b32_e32 v97, 1, v191
	v_add3_u32 v109, s4, v96, v97
	ds_read_b128 v[96:99], v104 offset:30720
	s_waitcnt lgkmcnt(1)
	v_mfma_f32_32x32x16_bf16 v[0:15], v[36:39], v[100:103], v[0:15]
	v_lshlrev_b32_e32 v100, 4, v189
	v_and_b32_e32 v176, 0x70, v100
	ds_read_b128 v[100:103], v104 offset:31232
	v_add_u32_e32 v147, s4, v176
	v_lshl_add_u32 v122, v125, 7, v147
	v_lshl_add_u64 v[142:143], s[12:13], 0, v[176:177]
	v_lshlrev_b32_e32 v176, 11, v125
	s_waitcnt lgkmcnt(1)
; __device__ __forceinline__ int crow(int r,int hi){return (r&3)+8*(r>>2)+4*hi;}
; #define XLAS __attribute__((address_space(3)))
; __device__ __forceinline__ int crow(int r, int hi) { return (r & 3) + 8 * (r >> 2) + 4 * hi; }
; __device__ __forceinline__ unsigned pk(float lo, float hi) { return pg8::cvt_pk_bf16(lo, hi); }
; #define X_STOREV(buf) do { _Pragma("unroll") for (int i_ = 0; i_ < 4; ++i_) *(XLAS u32x4*)(lds + (buf) + (wid + 8 * i_) * 1024 + lane * 16) = st[i_]; } while (0)
; __device__ __forceinline__ void unit(int b, int h, int qblk, const bf16_t* __restrict__ CQ, const bf16_t* __restrict__ CK, const bf16_t* __restrict__ CVT, bf16_t* __restrict__ CO, XLAS unsigned char* lds, const int wv) {
;     ...
; #pragma unroll
;         for (int r = 0; r < 16; ++r) { const int orow = crow(r, hi);
; #pragma unroll
;             for (int dt = 0; dt < 2; ++dt) { const unsigned w = pk(o[dt][r] * rli[r], 0.f); stg[orow * 64 + dt * 32 + r32] = (bf16_t)(w & 0xffffu); } }
;         asm volatile("s_waitcnt lgkmcnt(0)" ::: "memory");
; #pragma unroll
;         for (int i = 0; i < 4; ++i) { const int row = i * 8 + (lane >> 3), ch = lane & 7; const u32x4 v = *(const XLAS u32x4*)(stg + row * 64 + ch * 8); *(u32x4*)(Ow + (size_t)row * 1024 + c * 64 + ch * 8) = v; }
;         asm volatile("s_waitcnt lgkmcnt(0)" ::: "memory");
;         if (c < 3) X_STOREV(nbuf);
;         __syncthreads();
	v_mfma_f32_32x32x16_bf16 v[16:31], v[32:35], v[96:99], v[16:31]
	v_add_co_u32_e32 v96, vcc, s23, v144
	s_nop 1
	v_addc_co_u32_e32 v97, vcc, 0, v145, vcc
	v_lshl_add_u64 v[96:97], v[142:143], 0, v[176:177]
	s_waitcnt lgkmcnt(0)
	v_mfma_f32_32x32x16_bf16 v[0:15], v[32:35], v[100:103], v[0:15]
	s_nop 0
	v_mul_f32_e32 v16, v121, v16
	v_cvt_pk_bf16_f32 v16, v16, v177
	ds_write_b16 v109, v16
	s_nop 8
	v_mul_f32_e32 v0, v121, v0
	v_cvt_pk_bf16_f32 v0, v0, v177
	ds_write_b16 v109, v0 offset:64
	v_mul_f32_e32 v0, v120, v17
	v_cvt_pk_bf16_f32 v0, v0, v177
	ds_write_b16 v109, v0 offset:128
	v_mul_f32_e32 v0, v120, v1
	v_cvt_pk_bf16_f32 v0, v0, v177
	ds_write_b16 v109, v0 offset:192
	v_mul_f32_e32 v0, v119, v18
	v_cvt_pk_bf16_f32 v0, v0, v177
	ds_write_b16 v109, v0 offset:256
	v_mul_f32_e32 v0, v119, v2
	v_cvt_pk_bf16_f32 v0, v0, v177
	ds_write_b16 v109, v0 offset:320
	v_mul_f32_e32 v0, v118, v19
	v_cvt_pk_bf16_f32 v0, v0, v177
	ds_write_b16 v109, v0 offset:384
	v_mul_f32_e32 v0, v118, v3
	v_cvt_pk_bf16_f32 v0, v0, v177
	ds_write_b16 v109, v0 offset:448
	v_mul_f32_e32 v0, v117, v20
	v_cvt_pk_bf16_f32 v0, v0, v177
	ds_write_b16 v109, v0 offset:1024
	v_mul_f32_e32 v0, v117, v4
	v_cvt_pk_bf16_f32 v0, v0, v177
	ds_write_b16 v109, v0 offset:1088
	v_mul_f32_e32 v0, v116, v21
	v_cvt_pk_bf16_f32 v0, v0, v177
	ds_write_b16 v109, v0 offset:1152
	v_mul_f32_e32 v0, v116, v5
	v_cvt_pk_bf16_f32 v0, v0, v177
	ds_write_b16 v109, v0 offset:1216
	v_mul_f32_e32 v0, v115, v22
	v_cvt_pk_bf16_f32 v0, v0, v177
	ds_write_b16 v109, v0 offset:1280
	v_mul_f32_e32 v0, v115, v6
	v_cvt_pk_bf16_f32 v0, v0, v177
	ds_write_b16 v109, v0 offset:1344
	v_mul_f32_e32 v0, v113, v23
	v_cvt_pk_bf16_f32 v0, v0, v177
	ds_write_b16 v109, v0 offset:1408
	v_mul_f32_e32 v0, v113, v7
	v_cvt_pk_bf16_f32 v0, v0, v177
	ds_write_b16 v109, v0 offset:1472
	v_mul_f32_e32 v0, v114, v24
	v_cvt_pk_bf16_f32 v0, v0, v177
	ds_write_b16 v109, v0 offset:2048
	v_mul_f32_e32 v0, v114, v8
	v_cvt_pk_bf16_f32 v0, v0, v177
	ds_write_b16 v109, v0 offset:2112
	v_mul_f32_e32 v0, v112, v25
	v_cvt_pk_bf16_f32 v0, v0, v177
	ds_write_b16 v109, v0 offset:2176
	v_mul_f32_e32 v0, v112, v9
	v_cvt_pk_bf16_f32 v0, v0, v177
	ds_write_b16 v109, v0 offset:2240
	v_mul_f32_e32 v0, v111, v26
	v_cvt_pk_bf16_f32 v0, v0, v177
	ds_write_b16 v109, v0 offset:2304
	v_mul_f32_e32 v0, v111, v10
	v_cvt_pk_bf16_f32 v0, v0, v177
	ds_write_b16 v109, v0 offset:2368
	v_mul_f32_e32 v0, v110, v27
	v_cvt_pk_bf16_f32 v0, v0, v177
	ds_write_b16 v109, v0 offset:2432
	v_mul_f32_e32 v0, v110, v11
	v_cvt_pk_bf16_f32 v0, v0, v177
	ds_write_b16 v109, v0 offset:2496
	v_mul_f32_e32 v0, v108, v28
	v_cvt_pk_bf16_f32 v0, v0, v177
	ds_write_b16 v109, v0 offset:3072
	v_mul_f32_e32 v0, v108, v12
	v_cvt_pk_bf16_f32 v0, v0, v177
	ds_write_b16 v109, v0 offset:3136
	v_mul_f32_e32 v0, v107, v29
	v_cvt_pk_bf16_f32 v0, v0, v177
	ds_write_b16 v109, v0 offset:3200
	v_mul_f32_e32 v0, v107, v13
	v_cvt_pk_bf16_f32 v0, v0, v177
	ds_write_b16 v109, v0 offset:3264
	v_mul_f32_e32 v0, v106, v30
	v_cvt_pk_bf16_f32 v0, v0, v177
	ds_write_b16 v109, v0 offset:3328
	v_mul_f32_e32 v0, v106, v14
	v_cvt_pk_bf16_f32 v0, v0, v177
	ds_write_b16 v109, v0 offset:3392
	v_mul_f32_e32 v0, v105, v31
	v_cvt_pk_bf16_f32 v0, v0, v177
	ds_write_b16 v109, v0 offset:3456
	v_mul_f32_e32 v0, v105, v15
	v_cvt_pk_bf16_f32 v0, v0, v177
	ds_write_b16 v109, v0 offset:3520
	v_or_b32_e32 v8, 8, v125
	s_waitcnt lgkmcnt(0)
	v_lshl_add_u32 v123, v8, 7, v147
	ds_read_b128 v[0:3], v122
	ds_read_b128 v[4:7], v123
	v_lshlrev_b32_e32 v176, 11, v8
	v_lshl_add_u64 v[98:99], v[142:143], 0, v[176:177]
	v_or_b32_e32 v8, 24, v125
	s_waitcnt lgkmcnt(1)
	global_store_dwordx4 v[96:97], v[0:3], off
	s_waitcnt lgkmcnt(0)
	global_store_dwordx4 v[98:99], v[4:7], off
	s_nop 1
	v_or_b32_e32 v4, 16, v125
	v_lshl_add_u32 v124, v4, 7, v147
	v_lshl_add_u32 v125, v8, 7, v147
	ds_read_b128 v[0:3], v124
	v_lshlrev_b32_e32 v176, 11, v4
	ds_read_b128 v[4:7], v125
	v_lshl_add_u64 v[100:101], v[142:143], 0, v[176:177]
	v_lshlrev_b32_e32 v176, 11, v8
	v_lshl_add_u64 v[102:103], v[142:143], 0, v[176:177]
	s_waitcnt lgkmcnt(1)
	global_store_dwordx4 v[100:101], v[0:3], off
	s_waitcnt lgkmcnt(0)
	global_store_dwordx4 v[102:103], v[4:7], off
	s_waitcnt lgkmcnt(0)
	s_waitcnt vmcnt(7)
	ds_write_b128 v146, v[226:229] offset:32768
	s_waitcnt vmcnt(6)
	ds_write_b128 v146, v[230:233] offset:40960
	s_waitcnt vmcnt(5)
	ds_write_b128 v146, v[234:237] offset:49152
	s_waitcnt vmcnt(4)
	ds_write_b128 v146, v[238:241] offset:57344
	s_waitcnt lgkmcnt(0)
	s_barrier
; #define XLAS __attribute__((address_space(3)))
; #define X_LOADV(c)  do { _Pragma("unroll") for (int i_ = 0; i_ < 4; ++i_) st[i_] = *(const u32x4*)(Vg + (size_t)(c) * 64 * 2048 + i_ * 64); } while (0)
; __device__ __forceinline__ void unit(int b, int h, int qblk, const bf16_t* __restrict__ CQ, const bf16_t* __restrict__ CK, const bf16_t* __restrict__ CVT, bf16_t* __restrict__ CO, XLAS unsigned char* lds, const int wv) {
;     ...
;     for (int c = 0; c < 4; ++c) {
;         const int buf = (c & 1) ? XB1 : XB0, nbuf = (c & 1) ? XB0 : XB1;
;         if (c < 3) X_LOADV(c + 1);
;         f32x16 o[2]; o[0] = f32x16{}; o[1] = f32x16{};
; #pragma unroll
;         for (int j = 0; j < 16; ++j)
; #pragma unroll
;             for (int dt = 0; dt < 2; ++dt) {
;                 const bf16x8 vf = *(const XLAS bf16x8*)(lds + buf + voff + dt * 512 + j * 2048);
;                 o[dt] = __builtin_amdgcn_mfma_f32_32x32x16_bf16(__builtin_bit_cast(bf16x8, pw[j]), vf, o[dt], 0, 0, 0);
;             }
	ds_read_b128 v[126:129], v104 offset:32768
	ds_read_b128 v[130:133], v104 offset:33280
	ds_read_b128 v[244:247], v104 offset:34816
	ds_read_b128 v[248:251], v104 offset:35328
	ds_read_b128 v[148:151], v104 offset:36864
	s_waitcnt lgkmcnt(4)
	v_mfma_f32_32x32x16_bf16 v[16:31], v[92:95], v[126:129], 0
	v_add_co_u32_e32 v142, vcc, s25, v144
	s_nop 1
	v_addc_co_u32_e32 v143, vcc, 0, v145, vcc
	global_load_dwordx4 v[226:229], v[142:143], off
	global_load_dwordx4 v[230:233], v[142:143], off offset:128
	global_load_dwordx4 v[234:237], v[142:143], off offset:256
	global_load_dwordx4 v[238:241], v[142:143], off offset:384
	ds_read_b128 v[152:155], v104 offset:37376
	s_waitcnt lgkmcnt(4)
	v_mfma_f32_32x32x16_bf16 v[0:15], v[92:95], v[130:133], 0
	ds_read_b128 v[126:129], v104 offset:38912
	s_waitcnt lgkmcnt(4)
	v_mfma_f32_32x32x16_bf16 v[16:31], v[88:91], v[244:247], v[16:31]
	ds_read_b128 v[130:133], v104 offset:39424
	s_waitcnt lgkmcnt(4)
	v_mfma_f32_32x32x16_bf16 v[0:15], v[88:91], v[248:251], v[0:15]
	ds_read_b128 v[244:247], v104 offset:40960
	s_waitcnt lgkmcnt(4)
	v_mfma_f32_32x32x16_bf16 v[16:31], v[84:87], v[148:151], v[16:31]
	ds_read_b128 v[248:251], v104 offset:41472
	s_waitcnt lgkmcnt(4)
	v_mfma_f32_32x32x16_bf16 v[0:15], v[84:87], v[152:155], v[0:15]
	ds_read_b128 v[148:151], v104 offset:43008
	s_waitcnt lgkmcnt(4)
	v_mfma_f32_32x32x16_bf16 v[16:31], v[80:83], v[126:129], v[16:31]
	ds_read_b128 v[152:155], v104 offset:43520
	s_waitcnt lgkmcnt(4)
	v_mfma_f32_32x32x16_bf16 v[0:15], v[80:83], v[130:133], v[0:15]
	ds_read_b128 v[126:129], v104 offset:45056
	s_waitcnt lgkmcnt(4)
	v_mfma_f32_32x32x16_bf16 v[16:31], v[76:79], v[244:247], v[16:31]
	ds_read_b128 v[130:133], v104 offset:45568
	s_waitcnt lgkmcnt(4)
	v_mfma_f32_32x32x16_bf16 v[0:15], v[76:79], v[248:251], v[0:15]
	ds_read_b128 v[244:247], v104 offset:47104
	s_waitcnt lgkmcnt(4)
	v_mfma_f32_32x32x16_bf16 v[16:31], v[72:75], v[148:151], v[16:31]
	ds_read_b128 v[248:251], v104 offset:47616
	s_waitcnt lgkmcnt(4)
	v_mfma_f32_32x32x16_bf16 v[0:15], v[72:75], v[152:155], v[0:15]
	ds_read_b128 v[148:151], v104 offset:49152
	s_waitcnt lgkmcnt(4)
	v_mfma_f32_32x32x16_bf16 v[16:31], v[68:71], v[126:129], v[16:31]
	ds_read_b128 v[152:155], v104 offset:49664
	s_waitcnt lgkmcnt(4)
	v_mfma_f32_32x32x16_bf16 v[0:15], v[68:71], v[130:133], v[0:15]
	ds_read_b128 v[126:129], v104 offset:51200
	s_waitcnt lgkmcnt(4)
	v_mfma_f32_32x32x16_bf16 v[16:31], v[64:67], v[244:247], v[16:31]
	ds_read_b128 v[130:133], v104 offset:51712
	s_waitcnt lgkmcnt(4)
	v_mfma_f32_32x32x16_bf16 v[0:15], v[64:67], v[248:251], v[0:15]
	ds_read_b128 v[244:247], v104 offset:53248
	s_waitcnt lgkmcnt(4)
	v_mfma_f32_32x32x16_bf16 v[16:31], v[60:63], v[148:151], v[16:31]
	ds_read_b128 v[248:251], v104 offset:53760
	s_waitcnt lgkmcnt(4)
	v_mfma_f32_32x32x16_bf16 v[0:15], v[60:63], v[152:155], v[0:15]
	ds_read_b128 v[148:151], v104 offset:55296
	s_waitcnt lgkmcnt(4)
	v_mfma_f32_32x32x16_bf16 v[16:31], v[56:59], v[126:129], v[16:31]
	ds_read_b128 v[152:155], v104 offset:55808
	s_waitcnt lgkmcnt(4)
	v_mfma_f32_32x32x16_bf16 v[0:15], v[56:59], v[130:133], v[0:15]
	ds_read_b128 v[126:129], v104 offset:57344
	s_waitcnt lgkmcnt(4)
	v_mfma_f32_32x32x16_bf16 v[16:31], v[52:55], v[244:247], v[16:31]
	ds_read_b128 v[130:133], v104 offset:57856
	s_waitcnt lgkmcnt(4)
	v_mfma_f32_32x32x16_bf16 v[0:15], v[52:55], v[248:251], v[0:15]
	ds_read_b128 v[244:247], v104 offset:59392
	s_waitcnt lgkmcnt(4)
	v_mfma_f32_32x32x16_bf16 v[16:31], v[48:51], v[148:151], v[16:31]
	ds_read_b128 v[248:251], v104 offset:59904
	s_waitcnt lgkmcnt(4)
	v_mfma_f32_32x32x16_bf16 v[0:15], v[48:51], v[152:155], v[0:15]
	ds_read_b128 v[148:151], v104 offset:61440
	s_waitcnt lgkmcnt(4)
	v_mfma_f32_32x32x16_bf16 v[16:31], v[44:47], v[126:129], v[16:31]
	ds_read_b128 v[152:155], v104 offset:61952
	s_waitcnt lgkmcnt(4)
	v_mfma_f32_32x32x16_bf16 v[0:15], v[44:47], v[130:133], v[0:15]
	ds_read_b128 v[126:129], v104 offset:63488
	s_waitcnt lgkmcnt(4)
	v_mfma_f32_32x32x16_bf16 v[16:31], v[40:43], v[244:247], v[16:31]
	ds_read_b128 v[130:133], v104 offset:64000
	s_waitcnt lgkmcnt(4)
	v_mfma_f32_32x32x16_bf16 v[0:15], v[40:43], v[248:251], v[0:15]
	s_waitcnt lgkmcnt(3)
	v_mfma_f32_32x32x16_bf16 v[16:31], v[36:39], v[148:151], v[16:31]
	s_waitcnt lgkmcnt(2)
	v_mfma_f32_32x32x16_bf16 v[0:15], v[36:39], v[152:155], v[0:15]
	s_waitcnt lgkmcnt(1)
	v_mfma_f32_32x32x16_bf16 v[16:31], v[32:35], v[126:129], v[16:31]
	v_add_co_u32_e32 v142, vcc, s26, v144
	s_nop 6
	v_mul_f32_e32 v16, v121, v16
	s_waitcnt lgkmcnt(0)
; __device__ __forceinline__ int crow(int r,int hi){return (r&3)+8*(r>>2)+4*hi;}
; #define XLAS __attribute__((address_space(3)))
; __device__ __forceinline__ int crow(int r, int hi) { return (r & 3) + 8 * (r >> 2) + 4 * hi; }
; __device__ __forceinline__ unsigned pk(float lo, float hi) { return pg8::cvt_pk_bf16(lo, hi); }
; #define X_LOADV(c)  do { _Pragma("unroll") for (int i_ = 0; i_ < 4; ++i_) st[i_] = *(const u32x4*)(Vg + (size_t)(c) * 64 * 2048 + i_ * 64); } while (0)
; #define X_STOREV(buf) do { _Pragma("unroll") for (int i_ = 0; i_ < 4; ++i_) *(XLAS u32x4*)(lds + (buf) + (wid + 8 * i_) * 1024 + lane * 16) = st[i_]; } while (0)
; __device__ __forceinline__ void unit(int b, int h, int qblk, const bf16_t* __restrict__ CQ, const bf16_t* __restrict__ CK, const bf16_t* __restrict__ CVT, bf16_t* __restrict__ CO, XLAS unsigned char* lds, const int wv) {
;     ...
;     for (int c = 0; c < 4; ++c) {
;         const int buf = (c & 1) ? XB1 : XB0, nbuf = (c & 1) ? XB0 : XB1;
;         if (c < 3) X_LOADV(c + 1);
;         f32x16 o[2]; o[0] = f32x16{}; o[1] = f32x16{};
; #pragma unroll
;         for (int j = 0; j < 16; ++j)
; #pragma unroll
;             for (int dt = 0; dt < 2; ++dt) {
;                 const bf16x8 vf = *(const XLAS bf16x8*)(lds + buf + voff + dt * 512 + j * 2048);
;     ...
; #pragma unroll
;         for (int r = 0; r < 16; ++r) { const int orow = crow(r, hi);
; #pragma unroll
;             for (int dt = 0; dt < 2; ++dt) { const unsigned w = pk(o[dt][r] * rli[r], 0.f); stg[orow * 64 + dt * 32 + r32] = (bf16_t)(w & 0xffffu); } }
;         asm volatile("s_waitcnt lgkmcnt(0)" ::: "memory");
; #pragma unroll
;         for (int i = 0; i < 4; ++i) { const int row = i * 8 + (lane >> 3), ch = lane & 7; const u32x4 v = *(const XLAS u32x4*)(stg + row * 64 + ch * 8); *(u32x4*)(Ow + (size_t)row * 1024 + c * 64 + ch * 8) = v; }
;         asm volatile("s_waitcnt lgkmcnt(0)" ::: "memory");
;         if (c < 3) X_STOREV(nbuf);
;         __syncthreads();
	v_mfma_f32_32x32x16_bf16 v[0:15], v[32:35], v[130:133], v[0:15]
	v_cvt_pk_bf16_f32 v16, v16, v177
	ds_write_b16 v109, v16
	v_addc_co_u32_e32 v143, vcc, 0, v145, vcc
	s_nop 9
	v_mul_f32_e32 v0, v121, v0
	v_cvt_pk_bf16_f32 v0, v0, v177
	ds_write_b16 v109, v0 offset:64
	v_mul_f32_e32 v0, v120, v17
	v_cvt_pk_bf16_f32 v0, v0, v177
	ds_write_b16 v109, v0 offset:128
	v_mul_f32_e32 v0, v120, v1
	v_cvt_pk_bf16_f32 v0, v0, v177
	ds_write_b16 v109, v0 offset:192
	v_mul_f32_e32 v0, v119, v18
	v_cvt_pk_bf16_f32 v0, v0, v177
	ds_write_b16 v109, v0 offset:256
	v_mul_f32_e32 v0, v119, v2
	v_cvt_pk_bf16_f32 v0, v0, v177
	ds_write_b16 v109, v0 offset:320
	v_mul_f32_e32 v0, v118, v19
	v_cvt_pk_bf16_f32 v0, v0, v177
	ds_write_b16 v109, v0 offset:384
	v_mul_f32_e32 v0, v118, v3
	v_cvt_pk_bf16_f32 v0, v0, v177
	ds_write_b16 v109, v0 offset:448
	v_mul_f32_e32 v0, v117, v20
	v_cvt_pk_bf16_f32 v0, v0, v177
	ds_write_b16 v109, v0 offset:1024
	v_mul_f32_e32 v0, v117, v4
	v_cvt_pk_bf16_f32 v0, v0, v177
	ds_write_b16 v109, v0 offset:1088
	v_mul_f32_e32 v0, v116, v21
	v_cvt_pk_bf16_f32 v0, v0, v177
	ds_write_b16 v109, v0 offset:1152
	v_mul_f32_e32 v0, v116, v5
	v_cvt_pk_bf16_f32 v0, v0, v177
	ds_write_b16 v109, v0 offset:1216
	v_mul_f32_e32 v0, v115, v22
	v_cvt_pk_bf16_f32 v0, v0, v177
	ds_write_b16 v109, v0 offset:1280
	v_mul_f32_e32 v0, v115, v6
	v_cvt_pk_bf16_f32 v0, v0, v177
	ds_write_b16 v109, v0 offset:1344
	v_mul_f32_e32 v0, v113, v23
	v_cvt_pk_bf16_f32 v0, v0, v177
	ds_write_b16 v109, v0 offset:1408
	v_mul_f32_e32 v0, v113, v7
	v_cvt_pk_bf16_f32 v0, v0, v177
	ds_write_b16 v109, v0 offset:1472
	v_mul_f32_e32 v0, v114, v24
	v_cvt_pk_bf16_f32 v0, v0, v177
	ds_write_b16 v109, v0 offset:2048
	v_mul_f32_e32 v0, v114, v8
	v_cvt_pk_bf16_f32 v0, v0, v177
	ds_write_b16 v109, v0 offset:2112
	v_mul_f32_e32 v0, v112, v25
	v_cvt_pk_bf16_f32 v0, v0, v177
	ds_write_b16 v109, v0 offset:2176
	v_mul_f32_e32 v0, v112, v9
	v_cvt_pk_bf16_f32 v0, v0, v177
	ds_write_b16 v109, v0 offset:2240
	v_mul_f32_e32 v0, v111, v26
	v_cvt_pk_bf16_f32 v0, v0, v177
	ds_write_b16 v109, v0 offset:2304
	v_mul_f32_e32 v0, v111, v10
	v_cvt_pk_bf16_f32 v0, v0, v177
	ds_write_b16 v109, v0 offset:2368
	v_mul_f32_e32 v0, v110, v27
	v_cvt_pk_bf16_f32 v0, v0, v177
	ds_write_b16 v109, v0 offset:2432
	v_mul_f32_e32 v0, v110, v11
	v_cvt_pk_bf16_f32 v0, v0, v177
	ds_write_b16 v109, v0 offset:2496
	v_mul_f32_e32 v0, v108, v28
	v_cvt_pk_bf16_f32 v0, v0, v177
	ds_write_b16 v109, v0 offset:3072
	v_mul_f32_e32 v0, v108, v12
	v_cvt_pk_bf16_f32 v0, v0, v177
	ds_write_b16 v109, v0 offset:3136
	v_mul_f32_e32 v0, v107, v29
	v_cvt_pk_bf16_f32 v0, v0, v177
	ds_write_b16 v109, v0 offset:3200
	v_mul_f32_e32 v0, v107, v13
	v_cvt_pk_bf16_f32 v0, v0, v177
	ds_write_b16 v109, v0 offset:3264
	v_mul_f32_e32 v0, v106, v30
	v_cvt_pk_bf16_f32 v0, v0, v177
	ds_write_b16 v109, v0 offset:3328
	v_mul_f32_e32 v0, v106, v14
	v_cvt_pk_bf16_f32 v0, v0, v177
	ds_write_b16 v109, v0 offset:3392
	v_mul_f32_e32 v0, v105, v31
	v_cvt_pk_bf16_f32 v0, v0, v177
	ds_write_b16 v109, v0 offset:3456
	v_mul_f32_e32 v0, v105, v15
	v_cvt_pk_bf16_f32 v0, v0, v177
	ds_write_b16 v109, v0 offset:3520
	s_waitcnt lgkmcnt(0)
	ds_read_b128 v[0:3], v122
	ds_read_b128 v[4:7], v123
	ds_read_b128 v[8:11], v124
	ds_read_b128 v[12:15], v125
	s_waitcnt lgkmcnt(3)
	global_store_dwordx4 v[96:97], v[0:3], off offset:128
	s_waitcnt lgkmcnt(2)
	global_store_dwordx4 v[98:99], v[4:7], off offset:128
	s_waitcnt lgkmcnt(1)
	global_store_dwordx4 v[100:101], v[8:11], off offset:128
	s_waitcnt lgkmcnt(0)
	global_store_dwordx4 v[102:103], v[12:15], off offset:128
	s_waitcnt lgkmcnt(0)
	s_waitcnt vmcnt(7)
	ds_write_b128 v146, v[226:229]
	s_waitcnt vmcnt(6)
	ds_write_b128 v146, v[230:233] offset:8192
	s_waitcnt vmcnt(5)
	ds_write_b128 v146, v[234:237] offset:16384
	s_waitcnt vmcnt(4)
	ds_write_b128 v146, v[238:241] offset:24576
	s_waitcnt lgkmcnt(0)
	s_barrier
	global_load_dwordx4 v[226:229], v[142:143], off
	global_load_dwordx4 v[230:233], v[142:143], off offset:128
	global_load_dwordx4 v[234:237], v[142:143], off offset:256
	global_load_dwordx4 v[238:241], v[142:143], off offset:384
	ds_read_b128 v[126:129], v104
	ds_read_b128 v[130:133], v104 offset:512
	ds_read_b128 v[244:247], v104 offset:2048
	ds_read_b128 v[248:251], v104 offset:2560
	ds_read_b128 v[148:151], v104 offset:4096
	s_waitcnt lgkmcnt(4)
	v_mfma_f32_32x32x16_bf16 v[16:31], v[92:95], v[126:129], 0
	ds_read_b128 v[152:155], v104 offset:4608
	s_waitcnt lgkmcnt(4)
	v_mfma_f32_32x32x16_bf16 v[0:15], v[92:95], v[130:133], 0
	ds_read_b128 v[126:129], v104 offset:6144
	s_waitcnt lgkmcnt(4)
	v_mfma_f32_32x32x16_bf16 v[16:31], v[88:91], v[244:247], v[16:31]
	ds_read_b128 v[130:133], v104 offset:6656
	s_waitcnt lgkmcnt(4)
	v_mfma_f32_32x32x16_bf16 v[0:15], v[88:91], v[248:251], v[0:15]
	ds_read_b128 v[244:247], v104 offset:8192
	s_waitcnt lgkmcnt(4)
	v_mfma_f32_32x32x16_bf16 v[16:31], v[84:87], v[148:151], v[16:31]
	ds_read_b128 v[248:251], v104 offset:8704
	s_waitcnt lgkmcnt(4)
	v_mfma_f32_32x32x16_bf16 v[0:15], v[84:87], v[152:155], v[0:15]
	ds_read_b128 v[148:151], v104 offset:10240
	s_waitcnt lgkmcnt(4)
	v_mfma_f32_32x32x16_bf16 v[16:31], v[80:83], v[126:129], v[16:31]
	ds_read_b128 v[152:155], v104 offset:10752
	s_waitcnt lgkmcnt(4)
	v_mfma_f32_32x32x16_bf16 v[0:15], v[80:83], v[130:133], v[0:15]
	ds_read_b128 v[126:129], v104 offset:12288
	s_waitcnt lgkmcnt(4)
	v_mfma_f32_32x32x16_bf16 v[16:31], v[76:79], v[244:247], v[16:31]
	ds_read_b128 v[130:133], v104 offset:12800
	s_waitcnt lgkmcnt(4)
	v_mfma_f32_32x32x16_bf16 v[0:15], v[76:79], v[248:251], v[0:15]
	ds_read_b128 v[244:247], v104 offset:14336
	s_waitcnt lgkmcnt(4)
; __device__ __forceinline__ int crow(int r,int hi){return (r&3)+8*(r>>2)+4*hi;}
; #define XLAS __attribute__((address_space(3)))
; __device__ __forceinline__ int crow(int r, int hi) { return (r & 3) + 8 * (r >> 2) + 4 * hi; }
; __device__ __forceinline__ unsigned pk(float lo, float hi) { return pg8::cvt_pk_bf16(lo, hi); }
; #define X_STOREV(buf) do { _Pragma("unroll") for (int i_ = 0; i_ < 4; ++i_) *(XLAS u32x4*)(lds + (buf) + (wid + 8 * i_) * 1024 + lane * 16) = st[i_]; } while (0)
; __device__ __forceinline__ void unit(int b, int h, int qblk, const bf16_t* __restrict__ CQ, const bf16_t* __restrict__ CK, const bf16_t* __restrict__ CVT, bf16_t* __restrict__ CO, XLAS unsigned char* lds, const int wv) {
;     ...
;         for (int j = 0; j < 16; ++j)
; #pragma unroll
;             for (int dt = 0; dt < 2; ++dt) {
;                 const bf16x8 vf = *(const XLAS bf16x8*)(lds + buf + voff + dt * 512 + j * 2048);
;                 o[dt] = __builtin_amdgcn_mfma_f32_32x32x16_bf16(__builtin_bit_cast(bf16x8, pw[j]), vf, o[dt], 0, 0, 0);
;             }
; #pragma unroll
;         for (int r = 0; r < 16; ++r) { const int orow = crow(r, hi);
; #pragma unroll
;             for (int dt = 0; dt < 2; ++dt) { const unsigned w = pk(o[dt][r] * rli[r], 0.f); stg[orow * 64 + dt * 32 + r32] = (bf16_t)(w & 0xffffu); } }
;         asm volatile("s_waitcnt lgkmcnt(0)" ::: "memory");
; #pragma unroll
;         for (int i = 0; i < 4; ++i) { const int row = i * 8 + (lane >> 3), ch = lane & 7; const u32x4 v = *(const XLAS u32x4*)(stg + row * 64 + ch * 8); *(u32x4*)(Ow + (size_t)row * 1024 + c * 64 + ch * 8) = v; }
;         asm volatile("s_waitcnt lgkmcnt(0)" ::: "memory");
;         if (c < 3) X_STOREV(nbuf);
;         __syncthreads();
	v_mfma_f32_32x32x16_bf16 v[16:31], v[72:75], v[148:151], v[16:31]
	ds_read_b128 v[248:251], v104 offset:14848
	s_waitcnt lgkmcnt(4)
	v_mfma_f32_32x32x16_bf16 v[0:15], v[72:75], v[152:155], v[0:15]
	ds_read_b128 v[148:151], v104 offset:16384
	s_waitcnt lgkmcnt(4)
	v_mfma_f32_32x32x16_bf16 v[16:31], v[68:71], v[126:129], v[16:31]
	ds_read_b128 v[152:155], v104 offset:16896
	s_waitcnt lgkmcnt(4)
	v_mfma_f32_32x32x16_bf16 v[0:15], v[68:71], v[130:133], v[0:15]
	ds_read_b128 v[126:129], v104 offset:18432
	s_waitcnt lgkmcnt(4)
	v_mfma_f32_32x32x16_bf16 v[16:31], v[64:67], v[244:247], v[16:31]
	ds_read_b128 v[130:133], v104 offset:18944
	s_waitcnt lgkmcnt(4)
	v_mfma_f32_32x32x16_bf16 v[0:15], v[64:67], v[248:251], v[0:15]
	ds_read_b128 v[244:247], v104 offset:20480
	s_waitcnt lgkmcnt(4)
	v_mfma_f32_32x32x16_bf16 v[16:31], v[60:63], v[148:151], v[16:31]
	ds_read_b128 v[248:251], v104 offset:20992
	s_waitcnt lgkmcnt(4)
	v_mfma_f32_32x32x16_bf16 v[0:15], v[60:63], v[152:155], v[0:15]
	ds_read_b128 v[148:151], v104 offset:22528
	s_waitcnt lgkmcnt(4)
	v_mfma_f32_32x32x16_bf16 v[16:31], v[56:59], v[126:129], v[16:31]
	ds_read_b128 v[152:155], v104 offset:23040
	s_waitcnt lgkmcnt(4)
	v_mfma_f32_32x32x16_bf16 v[0:15], v[56:59], v[130:133], v[0:15]
	ds_read_b128 v[126:129], v104 offset:24576
	s_waitcnt lgkmcnt(4)
	v_mfma_f32_32x32x16_bf16 v[16:31], v[52:55], v[244:247], v[16:31]
	ds_read_b128 v[130:133], v104 offset:25088
	s_waitcnt lgkmcnt(4)
	v_mfma_f32_32x32x16_bf16 v[0:15], v[52:55], v[248:251], v[0:15]
	ds_read_b128 v[244:247], v104 offset:26624
	s_waitcnt lgkmcnt(4)
	v_mfma_f32_32x32x16_bf16 v[16:31], v[48:51], v[148:151], v[16:31]
	ds_read_b128 v[248:251], v104 offset:27136
	s_waitcnt lgkmcnt(4)
	v_mfma_f32_32x32x16_bf16 v[0:15], v[48:51], v[152:155], v[0:15]
	ds_read_b128 v[148:151], v104 offset:28672
	s_waitcnt lgkmcnt(4)
	v_mfma_f32_32x32x16_bf16 v[16:31], v[44:47], v[126:129], v[16:31]
	ds_read_b128 v[152:155], v104 offset:29184
	s_waitcnt lgkmcnt(4)
	v_mfma_f32_32x32x16_bf16 v[0:15], v[44:47], v[130:133], v[0:15]
	ds_read_b128 v[126:129], v104 offset:30720
	s_waitcnt lgkmcnt(4)
	v_mfma_f32_32x32x16_bf16 v[16:31], v[40:43], v[244:247], v[16:31]
	ds_read_b128 v[130:133], v104 offset:31232
	s_waitcnt lgkmcnt(4)
	v_mfma_f32_32x32x16_bf16 v[0:15], v[40:43], v[248:251], v[0:15]
	s_waitcnt lgkmcnt(3)
	v_mfma_f32_32x32x16_bf16 v[16:31], v[36:39], v[148:151], v[16:31]
	s_waitcnt lgkmcnt(2)
	v_mfma_f32_32x32x16_bf16 v[0:15], v[36:39], v[152:155], v[0:15]
	s_waitcnt lgkmcnt(1)
	v_mfma_f32_32x32x16_bf16 v[16:31], v[32:35], v[126:129], v[16:31]
	s_nop 0
	s_nop 6
	v_mul_f32_e32 v16, v121, v16
	s_waitcnt lgkmcnt(0)
	v_mfma_f32_32x32x16_bf16 v[0:15], v[32:35], v[130:133], v[0:15]
	v_cvt_pk_bf16_f32 v16, v16, v177
	ds_write_b16 v109, v16
	s_nop 10
	v_mul_f32_e32 v0, v121, v0
	v_cvt_pk_bf16_f32 v0, v0, v177
	ds_write_b16 v109, v0 offset:64
	v_mul_f32_e32 v0, v120, v17
	v_cvt_pk_bf16_f32 v0, v0, v177
	ds_write_b16 v109, v0 offset:128
	v_mul_f32_e32 v0, v120, v1
	v_cvt_pk_bf16_f32 v0, v0, v177
	ds_write_b16 v109, v0 offset:192
	v_mul_f32_e32 v0, v119, v18
	v_cvt_pk_bf16_f32 v0, v0, v177
	ds_write_b16 v109, v0 offset:256
	v_mul_f32_e32 v0, v119, v2
	v_cvt_pk_bf16_f32 v0, v0, v177
	ds_write_b16 v109, v0 offset:320
	v_mul_f32_e32 v0, v118, v19
	v_cvt_pk_bf16_f32 v0, v0, v177
	ds_write_b16 v109, v0 offset:384
	v_mul_f32_e32 v0, v118, v3
	v_cvt_pk_bf16_f32 v0, v0, v177
	ds_write_b16 v109, v0 offset:448
	v_mul_f32_e32 v0, v117, v20
	v_cvt_pk_bf16_f32 v0, v0, v177
	ds_write_b16 v109, v0 offset:1024
	v_mul_f32_e32 v0, v117, v4
	v_cvt_pk_bf16_f32 v0, v0, v177
	ds_write_b16 v109, v0 offset:1088
	v_mul_f32_e32 v0, v116, v21
	v_cvt_pk_bf16_f32 v0, v0, v177
	ds_write_b16 v109, v0 offset:1152
	v_mul_f32_e32 v0, v116, v5
	v_cvt_pk_bf16_f32 v0, v0, v177
	ds_write_b16 v109, v0 offset:1216
	v_mul_f32_e32 v0, v115, v22
	v_cvt_pk_bf16_f32 v0, v0, v177
	ds_write_b16 v109, v0 offset:1280
	v_mul_f32_e32 v0, v115, v6
	v_cvt_pk_bf16_f32 v0, v0, v177
	ds_write_b16 v109, v0 offset:1344
	v_mul_f32_e32 v0, v113, v23
	v_cvt_pk_bf16_f32 v0, v0, v177
	ds_write_b16 v109, v0 offset:1408
	v_mul_f32_e32 v0, v113, v7
	v_cvt_pk_bf16_f32 v0, v0, v177
	ds_write_b16 v109, v0 offset:1472
	v_mul_f32_e32 v0, v114, v24
	v_cvt_pk_bf16_f32 v0, v0, v177
	ds_write_b16 v109, v0 offset:2048
	v_mul_f32_e32 v0, v114, v8
	v_cvt_pk_bf16_f32 v0, v0, v177
	ds_write_b16 v109, v0 offset:2112
	v_mul_f32_e32 v0, v112, v25
	v_cvt_pk_bf16_f32 v0, v0, v177
	ds_write_b16 v109, v0 offset:2176
	v_mul_f32_e32 v0, v112, v9
	v_cvt_pk_bf16_f32 v0, v0, v177
	ds_write_b16 v109, v0 offset:2240
	v_mul_f32_e32 v0, v111, v26
	v_cvt_pk_bf16_f32 v0, v0, v177
	ds_write_b16 v109, v0 offset:2304
	v_mul_f32_e32 v0, v111, v10
	v_cvt_pk_bf16_f32 v0, v0, v177
	ds_write_b16 v109, v0 offset:2368
	v_mul_f32_e32 v0, v110, v27
	v_cvt_pk_bf16_f32 v0, v0, v177
	ds_write_b16 v109, v0 offset:2432
	v_mul_f32_e32 v0, v110, v11
	v_cvt_pk_bf16_f32 v0, v0, v177
	ds_write_b16 v109, v0 offset:2496
	v_mul_f32_e32 v0, v108, v28
	v_cvt_pk_bf16_f32 v0, v0, v177
	ds_write_b16 v109, v0 offset:3072
	v_mul_f32_e32 v0, v108, v12
	v_cvt_pk_bf16_f32 v0, v0, v177
	ds_write_b16 v109, v0 offset:3136
	v_mul_f32_e32 v0, v107, v29
	v_cvt_pk_bf16_f32 v0, v0, v177
	ds_write_b16 v109, v0 offset:3200
	v_mul_f32_e32 v0, v107, v13
	v_cvt_pk_bf16_f32 v0, v0, v177
	ds_write_b16 v109, v0 offset:3264
	v_mul_f32_e32 v0, v106, v30
	v_cvt_pk_bf16_f32 v0, v0, v177
	ds_write_b16 v109, v0 offset:3328
	v_mul_f32_e32 v0, v106, v14
	v_cvt_pk_bf16_f32 v0, v0, v177
	ds_write_b16 v109, v0 offset:3392
	v_mul_f32_e32 v0, v105, v31
	v_cvt_pk_bf16_f32 v0, v0, v177
	ds_write_b16 v109, v0 offset:3456
	v_mul_f32_e32 v0, v105, v15
	v_cvt_pk_bf16_f32 v0, v0, v177
	ds_write_b16 v109, v0 offset:3520
	s_waitcnt lgkmcnt(0)
	ds_read_b128 v[0:3], v122
	ds_read_b128 v[4:7], v123
	ds_read_b128 v[8:11], v124
	ds_read_b128 v[12:15], v125
	s_waitcnt lgkmcnt(3)
	global_store_dwordx4 v[96:97], v[0:3], off offset:256
	s_waitcnt lgkmcnt(2)
	global_store_dwordx4 v[98:99], v[4:7], off offset:256
	s_waitcnt lgkmcnt(1)
	global_store_dwordx4 v[100:101], v[8:11], off offset:256
	s_waitcnt lgkmcnt(0)
	global_store_dwordx4 v[102:103], v[12:15], off offset:256
	s_waitcnt lgkmcnt(0)
	s_waitcnt vmcnt(7)
	ds_write_b128 v146, v[226:229] offset:32768
	s_waitcnt vmcnt(6)
	ds_write_b128 v146, v[230:233] offset:40960
	s_waitcnt vmcnt(5)
	ds_write_b128 v146, v[234:237] offset:49152
	s_waitcnt vmcnt(4)
	ds_write_b128 v146, v[238:241] offset:57344
	s_waitcnt lgkmcnt(0)
	s_barrier
; __device__ __forceinline__ int crow(int r,int hi){return (r&3)+8*(r>>2)+4*hi;}
; #define XLAS __attribute__((address_space(3)))
; __device__ __forceinline__ int crow(int r, int hi) { return (r & 3) + 8 * (r >> 2) + 4 * hi; }
; __device__ __forceinline__ unsigned pk(float lo, float hi) { return pg8::cvt_pk_bf16(lo, hi); }
; #define X_LOADV(c)  do { _Pragma("unroll") for (int i_ = 0; i_ < 4; ++i_) st[i_] = *(const u32x4*)(Vg + (size_t)(c) * 64 * 2048 + i_ * 64); } while (0)
; __device__ __forceinline__ void unit(int b, int h, int qblk, const bf16_t* __restrict__ CQ, const bf16_t* __restrict__ CK, const bf16_t* __restrict__ CVT, bf16_t* __restrict__ CO, XLAS unsigned char* lds, const int wv) {
;     ...
;     for (int c = 0; c < 4; ++c) {
;         const int buf = (c & 1) ? XB1 : XB0, nbuf = (c & 1) ? XB0 : XB1;
;         if (c < 3) X_LOADV(c + 1);
;         f32x16 o[2]; o[0] = f32x16{}; o[1] = f32x16{};
; #pragma unroll
;         for (int j = 0; j < 16; ++j)
; #pragma unroll
;             for (int dt = 0; dt < 2; ++dt) {
;                 const bf16x8 vf = *(const XLAS bf16x8*)(lds + buf + voff + dt * 512 + j * 2048);
;                 o[dt] = __builtin_amdgcn_mfma_f32_32x32x16_bf16(__builtin_bit_cast(bf16x8, pw[j]), vf, o[dt], 0, 0, 0);
;             }
; #pragma unroll
;         for (int r = 0; r < 16; ++r) { const int orow = crow(r, hi);
; #pragma unroll
;             for (int dt = 0; dt < 2; ++dt) { const unsigned w = pk(o[dt][r] * rli[r], 0.f); stg[orow * 64 + dt * 32 + r32] = (bf16_t)(w & 0xffffu); } }
	ds_read_b128 v[126:129], v104 offset:32768
	ds_read_b128 v[244:247], v104 offset:33280
	ds_read_b128 v[248:251], v104 offset:34816
	ds_read_b128 v[148:151], v104 offset:35328
	ds_read_b128 v[152:155], v104 offset:36864
	s_waitcnt lgkmcnt(4)
	v_mfma_f32_32x32x16_bf16 v[16:31], v[92:95], v[126:129], 0
	ds_read_b128 v[156:159], v104 offset:37376
	s_waitcnt lgkmcnt(4)
	v_mfma_f32_32x32x16_bf16 v[0:15], v[92:95], v[244:247], 0
	ds_read_b128 v[126:129], v104 offset:38912
	s_waitcnt lgkmcnt(4)
	v_mfma_f32_32x32x16_bf16 v[16:31], v[88:91], v[248:251], v[16:31]
	ds_read_b128 v[244:247], v104 offset:39424
	s_waitcnt lgkmcnt(4)
	v_mfma_f32_32x32x16_bf16 v[0:15], v[88:91], v[148:151], v[0:15]
	ds_read_b128 v[248:251], v104 offset:40960
	s_waitcnt lgkmcnt(4)
	v_mfma_f32_32x32x16_bf16 v[16:31], v[84:87], v[152:155], v[16:31]
	ds_read_b128 v[148:151], v104 offset:41472
	s_waitcnt lgkmcnt(4)
	v_mfma_f32_32x32x16_bf16 v[0:15], v[84:87], v[156:159], v[0:15]
	ds_read_b128 v[152:155], v104 offset:43008
	s_waitcnt lgkmcnt(4)
	v_mfma_f32_32x32x16_bf16 v[16:31], v[80:83], v[126:129], v[16:31]
	ds_read_b128 v[156:159], v104 offset:43520
	s_waitcnt lgkmcnt(4)
	v_mfma_f32_32x32x16_bf16 v[0:15], v[80:83], v[244:247], v[0:15]
	ds_read_b128 v[126:129], v104 offset:45056
	s_waitcnt lgkmcnt(4)
	v_mfma_f32_32x32x16_bf16 v[16:31], v[76:79], v[248:251], v[16:31]
	ds_read_b128 v[244:247], v104 offset:45568
	s_waitcnt lgkmcnt(4)
	v_mfma_f32_32x32x16_bf16 v[0:15], v[76:79], v[148:151], v[0:15]
	ds_read_b128 v[248:251], v104 offset:47104
	s_waitcnt lgkmcnt(4)
	v_mfma_f32_32x32x16_bf16 v[16:31], v[72:75], v[152:155], v[16:31]
	ds_read_b128 v[148:151], v104 offset:47616
	s_waitcnt lgkmcnt(4)
	v_mfma_f32_32x32x16_bf16 v[0:15], v[72:75], v[156:159], v[0:15]
	ds_read_b128 v[152:155], v104 offset:49152
	s_waitcnt lgkmcnt(4)
	v_mfma_f32_32x32x16_bf16 v[16:31], v[68:71], v[126:129], v[16:31]
	ds_read_b128 v[156:159], v104 offset:49664
	s_waitcnt lgkmcnt(4)
	v_mfma_f32_32x32x16_bf16 v[0:15], v[68:71], v[244:247], v[0:15]
	ds_read_b128 v[126:129], v104 offset:51200
	s_waitcnt lgkmcnt(4)
	v_mfma_f32_32x32x16_bf16 v[16:31], v[64:67], v[248:251], v[16:31]
	ds_read_b128 v[244:247], v104 offset:51712
	s_waitcnt lgkmcnt(4)
	v_mfma_f32_32x32x16_bf16 v[0:15], v[64:67], v[148:151], v[0:15]
	ds_read_b128 v[248:251], v104 offset:53248
	s_waitcnt lgkmcnt(4)
	v_mfma_f32_32x32x16_bf16 v[16:31], v[60:63], v[152:155], v[16:31]
	ds_read_b128 v[148:151], v104 offset:53760
	s_waitcnt lgkmcnt(4)
	v_mfma_f32_32x32x16_bf16 v[0:15], v[60:63], v[156:159], v[0:15]
	ds_read_b128 v[152:155], v104 offset:55296
	s_waitcnt lgkmcnt(4)
	v_mfma_f32_32x32x16_bf16 v[16:31], v[56:59], v[126:129], v[16:31]
	ds_read_b128 v[156:159], v104 offset:55808
	s_waitcnt lgkmcnt(4)
	v_mfma_f32_32x32x16_bf16 v[0:15], v[56:59], v[244:247], v[0:15]
	ds_read_b128 v[126:129], v104 offset:57344
	s_waitcnt lgkmcnt(4)
	v_mfma_f32_32x32x16_bf16 v[16:31], v[52:55], v[248:251], v[16:31]
	ds_read_b128 v[244:247], v104 offset:57856
	s_waitcnt lgkmcnt(4)
	v_mfma_f32_32x32x16_bf16 v[0:15], v[52:55], v[148:151], v[0:15]
	ds_read_b128 v[248:251], v104 offset:59392
	s_waitcnt lgkmcnt(4)
	v_mfma_f32_32x32x16_bf16 v[16:31], v[48:51], v[152:155], v[16:31]
	ds_read_b128 v[148:151], v104 offset:59904
	s_waitcnt lgkmcnt(4)
	v_mfma_f32_32x32x16_bf16 v[0:15], v[48:51], v[156:159], v[0:15]
	ds_read_b128 v[152:155], v104 offset:61440
	s_waitcnt lgkmcnt(4)
	v_mfma_f32_32x32x16_bf16 v[16:31], v[44:47], v[126:129], v[16:31]
	ds_read_b128 v[156:159], v104 offset:61952
	s_waitcnt lgkmcnt(4)
	v_mfma_f32_32x32x16_bf16 v[0:15], v[44:47], v[244:247], v[0:15]
	ds_read_b128 v[126:129], v104 offset:63488
	s_waitcnt lgkmcnt(4)
	v_mfma_f32_32x32x16_bf16 v[16:31], v[40:43], v[248:251], v[16:31]
	ds_read_b128 v[244:247], v104 offset:64000
	s_waitcnt lgkmcnt(4)
	v_mfma_f32_32x32x16_bf16 v[0:15], v[40:43], v[148:151], v[0:15]
	s_waitcnt lgkmcnt(3)
	v_mfma_f32_32x32x16_bf16 v[16:31], v[36:39], v[152:155], v[16:31]
	s_waitcnt lgkmcnt(2)
	v_mfma_f32_32x32x16_bf16 v[0:15], v[36:39], v[156:159], v[0:15]
	s_waitcnt lgkmcnt(1)
	v_mfma_f32_32x32x16_bf16 v[16:31], v[32:35], v[126:129], v[16:31]
	s_waitcnt lgkmcnt(0)
	v_mfma_f32_32x32x16_bf16 v[0:15], v[32:35], v[244:247], v[0:15]
	s_nop 9
	v_mul_f32_e32 v16, v121, v16
	v_cvt_pk_bf16_f32 v16, v16, v177
	ds_write_b16 v109, v16
	v_mul_f32_e32 v0, v121, v0
	v_cvt_pk_bf16_f32 v0, v0, v177
	ds_write_b16 v109, v0 offset:64
	v_mul_f32_e32 v0, v120, v17
	v_cvt_pk_bf16_f32 v0, v0, v177
	ds_write_b16 v109, v0 offset:128
	v_mul_f32_e32 v0, v120, v1
	v_cvt_pk_bf16_f32 v0, v0, v177
	ds_write_b16 v109, v0 offset:192
	v_mul_f32_e32 v0, v119, v18
	v_cvt_pk_bf16_f32 v0, v0, v177
	ds_write_b16 v109, v0 offset:256
	v_mul_f32_e32 v0, v119, v2
	v_cvt_pk_bf16_f32 v0, v0, v177
	ds_write_b16 v109, v0 offset:320
	v_mul_f32_e32 v0, v118, v19
	v_cvt_pk_bf16_f32 v0, v0, v177
	ds_write_b16 v109, v0 offset:384
	v_mul_f32_e32 v0, v118, v3
	v_cvt_pk_bf16_f32 v0, v0, v177
	ds_write_b16 v109, v0 offset:448
	v_mul_f32_e32 v0, v117, v20
	v_cvt_pk_bf16_f32 v0, v0, v177
	ds_write_b16 v109, v0 offset:1024
	v_mul_f32_e32 v0, v117, v4
	v_cvt_pk_bf16_f32 v0, v0, v177
	ds_write_b16 v109, v0 offset:1088
	v_mul_f32_e32 v0, v116, v21
	v_cvt_pk_bf16_f32 v0, v0, v177
	ds_write_b16 v109, v0 offset:1152
	v_mul_f32_e32 v0, v116, v5
	v_cvt_pk_bf16_f32 v0, v0, v177
	ds_write_b16 v109, v0 offset:1216
	v_mul_f32_e32 v0, v115, v22
	v_cvt_pk_bf16_f32 v0, v0, v177
	ds_write_b16 v109, v0 offset:1280
	v_mul_f32_e32 v0, v115, v6
	v_cvt_pk_bf16_f32 v0, v0, v177
	ds_write_b16 v109, v0 offset:1344
	v_mul_f32_e32 v0, v113, v23
	v_cvt_pk_bf16_f32 v0, v0, v177
	ds_write_b16 v109, v0 offset:1408
; __device__ __forceinline__ int mk_lane() { int l = (int)__builtin_amdgcn_mbcnt_hi(~0u, __builtin_amdgcn_mbcnt_lo(~0u, 0u)); asm volatile("" : "+v"(l)); return l; }
; __device__ __forceinline__ int crow(int r,int hi){return (r&3)+8*(r>>2)+4*hi;}
; #define XLAS __attribute__((address_space(3)))
; __device__ __forceinline__ int crow(int r, int hi) { return (r & 3) + 8 * (r >> 2) + 4 * hi; }
; __device__ __forceinline__ unsigned pk(float lo, float hi) { return pg8::cvt_pk_bf16(lo, hi); }
; __device__ __forceinline__ void unit(int b, int h, int qblk, const bf16_t* __restrict__ CQ, const bf16_t* __restrict__ CK, const bf16_t* __restrict__ CVT, bf16_t* __restrict__ CO, XLAS unsigned char* lds, const int wv) {
;     const int tid = wv * 64 + mk_lane(), lane = tid & 63, r32 = lane & 31, hi = lane >> 5; const int wid = __builtin_amdgcn_readfirstlane(tid >> 6);
;     const size_t qrow0 = (size_t)b * 4096 + (size_t)qblk * 256 + wid * 32;
;     const bf16_t* Qw = CQ + (qrow0 + r32) * 1024 + h * 256 + hi * 8;
;     const bf16_t* Kg = CK + ((size_t)b * 256 + lane) * 1024 + h * 256 + wid * 8;
;     const bf16_t* Vg = CVT + ((size_t)h * 256 + lane) * 2048 + (size_t)b * 256 + wid * 8;
;     u32x4 st[4];
;     ...
;     const int kswz = (r32 & ~12) | ((r32 & 4) << 1) | ((r32 & 8) >> 1);
;     const int koff = hi * 4096 + kswz * 16;
;     const int voff = hi * 1024 + r32 * 16;
;     f32x16 s[8];
; #pragma unroll
;     for (int kt = 0; kt < 8; ++kt) s[kt] = f32x16{};
;     X_LOADK(0);
;     bf16x8 qfa[4][4];
; #pragma unroll
;     for (int dc = 0; dc < 4; ++dc)
; #pragma unroll
;         for (int ks = 0; ks < 4; ++ks) qfa[dc][ks] = *(const bf16x8*)(Qw + dc * 64 + ks * 16);
;     X_STOREK(XB0);
;     __syncthreads();
;     ...
; #pragma unroll
;         for (int r = 0; r < 16; ++r) { const int orow = crow(r, hi);
; #pragma unroll
;             for (int dt = 0; dt < 2; ++dt) { const unsigned w = pk(o[dt][r] * rli[r], 0.f); stg[orow * 64 + dt * 32 + r32] = (bf16_t)(w & 0xffffu); } }
;         asm volatile("s_waitcnt lgkmcnt(0)" ::: "memory");
; #pragma unroll
;         for (int i = 0; i < 4; ++i) { const int row = i * 8 + (lane >> 3), ch = lane & 7; const u32x4 v = *(const XLAS u32x4*)(stg + row * 64 + ch * 8); *(u32x4*)(Ow + (size_t)row * 1024 + c * 64 + ch * 8) = v; }
;         asm volatile("s_waitcnt lgkmcnt(0)" ::: "memory");
;         if (c < 3) X_STOREV(nbuf);
;         __syncthreads();
	v_mul_f32_e32 v0, v113, v7
	v_cvt_pk_bf16_f32 v0, v0, v177
	ds_write_b16 v109, v0 offset:1472
	v_mul_f32_e32 v0, v114, v24
	v_cvt_pk_bf16_f32 v0, v0, v177
	ds_write_b16 v109, v0 offset:2048
	v_mul_f32_e32 v0, v114, v8
	v_cvt_pk_bf16_f32 v0, v0, v177
	ds_write_b16 v109, v0 offset:2112
	v_mul_f32_e32 v0, v112, v25
	v_cvt_pk_bf16_f32 v0, v0, v177
	ds_write_b16 v109, v0 offset:2176
	v_mul_f32_e32 v0, v112, v9
	v_cvt_pk_bf16_f32 v0, v0, v177
	ds_write_b16 v109, v0 offset:2240
	v_mul_f32_e32 v0, v111, v26
	v_cvt_pk_bf16_f32 v0, v0, v177
	ds_write_b16 v109, v0 offset:2304
	v_mul_f32_e32 v0, v111, v10
	v_cvt_pk_bf16_f32 v0, v0, v177
	ds_write_b16 v109, v0 offset:2368
	v_mul_f32_e32 v0, v110, v27
	v_cvt_pk_bf16_f32 v0, v0, v177
	ds_write_b16 v109, v0 offset:2432
	v_mul_f32_e32 v0, v110, v11
	v_cvt_pk_bf16_f32 v0, v0, v177
	ds_write_b16 v109, v0 offset:2496
	v_mul_f32_e32 v0, v108, v28
	v_cvt_pk_bf16_f32 v0, v0, v177
	ds_write_b16 v109, v0 offset:3072
	v_mul_f32_e32 v0, v108, v12
	v_cvt_pk_bf16_f32 v0, v0, v177
	ds_write_b16 v109, v0 offset:3136
	v_mul_f32_e32 v0, v107, v29
	v_cvt_pk_bf16_f32 v0, v0, v177
	ds_write_b16 v109, v0 offset:3200
	v_mul_f32_e32 v0, v107, v13
	v_cvt_pk_bf16_f32 v0, v0, v177
	ds_write_b16 v109, v0 offset:3264
	v_mul_f32_e32 v0, v106, v30
	v_cvt_pk_bf16_f32 v0, v0, v177
	ds_write_b16 v109, v0 offset:3328
	v_mul_f32_e32 v0, v106, v14
	v_cvt_pk_bf16_f32 v0, v0, v177
	ds_write_b16 v109, v0 offset:3392
	v_mul_f32_e32 v0, v105, v31
	v_cvt_pk_bf16_f32 v0, v0, v177
	ds_write_b16 v109, v0 offset:3456
	v_mul_f32_e32 v0, v105, v15
	v_cvt_pk_bf16_f32 v0, v0, v177
	ds_write_b16 v109, v0 offset:3520
	s_waitcnt lgkmcnt(0)
	ds_read_b128 v[0:3], v122
	ds_read_b128 v[4:7], v123
	ds_read_b128 v[8:11], v124
	ds_read_b128 v[12:15], v125
	s_waitcnt lgkmcnt(3)
	global_store_dwordx4 v[96:97], v[0:3], off offset:384
	s_waitcnt lgkmcnt(2)
	global_store_dwordx4 v[98:99], v[4:7], off offset:384
	s_waitcnt lgkmcnt(1)
	global_store_dwordx4 v[100:101], v[8:11], off offset:384
	s_waitcnt lgkmcnt(0)
	global_store_dwordx4 v[102:103], v[12:15], off offset:384
	s_waitcnt lgkmcnt(0)
	s_barrier
	s_cbranch_scc0 .LBB0_1147
.LBB0_1145:
	v_mov_b32_e32 v189, v212
	s_ashr_i32 s14, s2, 6
	s_ashr_i32 s15, s14, 31
	v_add_u32_e32 v0, s20, v189
	s_lshl_b64 s[12:13], s[14:15], 12
	v_readfirstlane_b32 s27, v0
	s_ashr_i32 s29, s27, 6
	s_and_b32 s4, s21, 0xf00
	s_or_b32 s4, s12, s4
	s_lshl_b32 s12, s29, 5
	s_bfe_u32 s28, s2, 0x20004
	s_ashr_i32 s16, s12, 31
	s_add_u32 s12, s4, s12
	v_and_b32_e32 v190, 63, v189
	s_addc_u32 s13, s13, s16
	s_lshl_b64 s[16:17], s[14:15], 19
	v_lshl_or_b32 v0, v190, 11, s16
	v_mov_b32_e32 v1, s17
	s_lshl_b32 s16, s29, 3
	v_lshl_add_u64 v[0:1], s[8:9], 0, v[0:1]
	s_ashr_i32 s17, s16, 31
	s_lshl_b32 s4, s28, 9
	v_lshl_add_u64 v[0:1], v[0:1], 0, s[4:5]
	s_lshl_b64 s[16:17], s[16:17], 1
	v_lshl_add_u64 v[180:181], v[0:1], 0, s[16:17]
	v_add_co_u32_e32 v182, vcc, s22, v180
	v_and_b32_e32 v191, 31, v189
	s_nop 0
	v_addc_co_u32_e32 v183, vcc, 0, v181, vcc
	v_add_co_u32_e32 v184, vcc, s23, v180
	global_load_dwordx4 v[0:3], v[180:181], off
	global_load_dwordx4 v[4:7], v[182:183], off
	v_addc_co_u32_e32 v185, vcc, 0, v181, vcc
	v_add_co_u32_e32 v186, vcc, s24, v180
	v_or_b32_e32 v16, s12, v191
	s_nop 0
	v_addc_co_u32_e32 v187, vcc, 0, v181, vcc
	global_load_dwordx4 v[8:11], v[184:185], off
	global_load_dwordx4 v[12:15], v[186:187], off
	v_mov_b32_e32 v17, s13
	v_lshlrev_b64 v[16:17], 11, v[16:17]
	s_lshl_b32 s30, s28, 20
	v_bfe_u32 v192, v189, 5, 1
	v_lshl_or_b32 v176, v190, 12, s30
	v_lshl_add_u64 v[16:17], s[6:7], 0, v[16:17]
	v_lshl_add_u64 v[178:179], s[10:11], 0, v[176:177]
	v_lshl_add_u64 v[16:17], v[16:17], 0, s[4:5]
	v_lshlrev_b32_e32 v176, 4, v192
	v_lshl_add_u64 v[16:17], v[16:17], 0, v[176:177]
	global_load_dwordx4 v[194:197], v[16:17], off
	global_load_dwordx4 v[198:201], v[16:17], off offset:32
	global_load_dwordx4 v[202:205], v[16:17], off offset:64
	global_load_dwordx4 v[206:209], v[16:17], off offset:96
	global_load_dwordx4 v[172:175], v[16:17], off offset:128
	global_load_dwordx4 v[168:171], v[16:17], off offset:160
	global_load_dwordx4 v[164:167], v[16:17], off offset:192
	global_load_dwordx4 v[160:163], v[16:17], off offset:224
	global_load_dwordx4 v[156:159], v[16:17], off offset:256
	global_load_dwordx4 v[152:155], v[16:17], off offset:288
	global_load_dwordx4 v[148:151], v[16:17], off offset:320
	global_load_dwordx4 v[144:147], v[16:17], off offset:352
	global_load_dwordx4 v[140:143], v[16:17], off offset:384
	global_load_dwordx4 v[136:139], v[16:17], off offset:416
	global_load_dwordx4 v[132:135], v[16:17], off offset:448
	global_load_dwordx4 v[128:131], v[16:17], off offset:480
	v_lshlrev_b32_e32 v18, 1, v189
	v_lshrrev_b32_e32 v19, 1, v189
	v_and_b32_e32 v20, 19, v189
	v_and_b32_e32 v18, 8, v18
	v_and_b32_e32 v19, 4, v19
	v_or3_b32 v18, v20, v18, v19
	s_lshl_b32 s4, s29, 12
	v_lshlrev_b32_e32 v21, 12, v192
	v_lshlrev_b32_e32 v193, 4, v190
	v_lshlrev_b32_e32 v18, 4, v18
	s_add_i32 s4, s4, 0
	v_add3_u32 v176, 0, v21, v18
	v_add_u32_e32 v210, s4, v193
	s_lshl_b64 s[14:15], s[14:15], 9
	v_cmp_gt_u32_e32 vcc, 32, v190
	s_waitcnt vmcnt(0)
	ds_write_b128 v210, v[0:3]
	ds_write_b128 v210, v[4:7] offset:1024
	ds_write_b128 v210, v[8:11] offset:2048
	ds_write_b128 v210, v[12:15] offset:3072
	s_waitcnt lgkmcnt(0)
	s_barrier
; #define XLAS __attribute__((address_space(3)))
; #define X_LOADK(dc) do { _Pragma("unroll") for (int i_ = 0; i_ < 4; ++i_) st[i_] = *(const u32x4*)(Kg + (dc) * 64 + (size_t)i_ * 64 * 1024); } while (0)
; #define X_LOADV(c)  do { _Pragma("unroll") for (int i_ = 0; i_ < 4; ++i_) st[i_] = *(const u32x4*)(Vg + (size_t)(c) * 64 * 2048 + i_ * 64); } while (0)
; #define X_STOREK(buf) do { _Pragma("unroll") for (int i_ = 0; i_ < 4; ++i_) *(XLAS u32x4*)(lds + (buf) + wid * 4096 + (64 * i_ + lane) * 16) = st[i_]; } while (0)
; #define X_STOREV(buf) do { _Pragma("unroll") for (int i_ = 0; i_ < 4; ++i_) *(XLAS u32x4*)(lds + (buf) + (wid + 8 * i_) * 1024 + lane * 16) = st[i_]; } while (0)
; __device__ __forceinline__ void unit(int b, int h, int qblk, const bf16_t* __restrict__ CQ, const bf16_t* __restrict__ CK, const bf16_t* __restrict__ CVT, bf16_t* __restrict__ CO, XLAS unsigned char* lds, const int wv) {
;     ...
; #pragma unroll
;     for (int dc = 0; dc < 4; ++dc) {
;         const int buf = (dc & 1) ? XB1 : XB0, nbuf = (dc & 1) ? XB0 : XB1;
;         if (dc < 3) X_LOADK(dc + 1); else X_LOADV(0);
; #pragma unroll
;         for (int kt = 0; kt < 8; ++kt)
; #pragma unroll
;             for (int ks = 0; ks < 4; ++ks) {
;                 const bf16x8 kf = *(const XLAS bf16x8*)(lds + buf + koff + kt * 512 + ks * 8192);
;                 s[kt] = __builtin_amdgcn_mfma_f32_32x32x16_bf16(kf, qfa[dc][ks], s[kt], 0, 0, 0);
;             }
;         if (dc < 3) X_STOREK(nbuf); else X_STOREV(nbuf);
;         __syncthreads();
;     }
	global_load_dwordx4 v[226:229], v[180:181], off offset:128
	global_load_dwordx4 v[230:233], v[182:183], off offset:128
	global_load_dwordx4 v[234:237], v[184:185], off offset:128
	global_load_dwordx4 v[238:241], v[186:187], off offset:128
	ds_read_b128 v[214:217], v176
	ds_read_b128 v[218:221], v176 offset:512
	ds_read_b128 v[244:247], v176 offset:1024
	ds_read_b128 v[248:251], v176 offset:1536
	s_waitcnt lgkmcnt(3)
	v_mfma_f32_32x32x16_bf16 v[112:127], v[214:217], v[194:197], 0
	ds_read_b128 v[214:217], v176 offset:8192
	s_waitcnt lgkmcnt(3)
	v_mfma_f32_32x32x16_bf16 v[96:111], v[218:221], v[194:197], 0
	ds_read_b128 v[218:221], v176 offset:8704
	s_waitcnt lgkmcnt(3)
	v_mfma_f32_32x32x16_bf16 v[80:95], v[244:247], v[194:197], 0
	ds_read_b128 v[244:247], v176 offset:9216
	s_waitcnt lgkmcnt(3)
	v_mfma_f32_32x32x16_bf16 v[64:79], v[248:251], v[194:197], 0
	ds_read_b128 v[248:251], v176 offset:9728
	s_waitcnt lgkmcnt(3)
	v_mfma_f32_32x32x16_bf16 v[112:127], v[214:217], v[198:201], v[112:127]
	ds_read_b128 v[214:217], v176 offset:16384
	s_waitcnt lgkmcnt(3)
	v_mfma_f32_32x32x16_bf16 v[96:111], v[218:221], v[198:201], v[96:111]
	ds_read_b128 v[218:221], v176 offset:16896
	s_waitcnt lgkmcnt(3)
	v_mfma_f32_32x32x16_bf16 v[80:95], v[244:247], v[198:201], v[80:95]
	ds_read_b128 v[244:247], v176 offset:17408
	s_waitcnt lgkmcnt(3)
	v_mfma_f32_32x32x16_bf16 v[64:79], v[248:251], v[198:201], v[64:79]
	ds_read_b128 v[248:251], v176 offset:17920
	s_waitcnt lgkmcnt(3)
	v_mfma_f32_32x32x16_bf16 v[112:127], v[214:217], v[202:205], v[112:127]
	ds_read_b128 v[214:217], v176 offset:24576
	s_waitcnt lgkmcnt(3)
	v_mfma_f32_32x32x16_bf16 v[96:111], v[218:221], v[202:205], v[96:111]
	ds_read_b128 v[218:221], v176 offset:25088
	s_waitcnt lgkmcnt(3)
	v_mfma_f32_32x32x16_bf16 v[80:95], v[244:247], v[202:205], v[80:95]
	ds_read_b128 v[244:247], v176 offset:25600
	s_waitcnt lgkmcnt(3)
	v_mfma_f32_32x32x16_bf16 v[64:79], v[248:251], v[202:205], v[64:79]
	ds_read_b128 v[248:251], v176 offset:26112
	s_waitcnt lgkmcnt(3)
	v_mfma_f32_32x32x16_bf16 v[112:127], v[214:217], v[206:209], v[112:127]
	ds_read_b128 v[214:217], v176 offset:2048
	s_waitcnt lgkmcnt(3)
	v_mfma_f32_32x32x16_bf16 v[96:111], v[218:221], v[206:209], v[96:111]
	ds_read_b128 v[218:221], v176 offset:2560
	s_waitcnt lgkmcnt(3)
	v_mfma_f32_32x32x16_bf16 v[80:95], v[244:247], v[206:209], v[80:95]
	ds_read_b128 v[244:247], v176 offset:10240
	s_waitcnt lgkmcnt(3)
	v_mfma_f32_32x32x16_bf16 v[64:79], v[248:251], v[206:209], v[64:79]
	ds_read_b128 v[248:251], v176 offset:10752
	s_waitcnt lgkmcnt(3)
	v_mfma_f32_32x32x16_bf16 v[48:63], v[214:217], v[194:197], 0
	ds_read_b128 v[214:217], v176 offset:18432
	s_waitcnt lgkmcnt(3)
	v_mfma_f32_32x32x16_bf16 v[32:47], v[218:221], v[194:197], 0
	ds_read_b128 v[218:221], v176 offset:18944
	s_waitcnt lgkmcnt(3)
	v_mfma_f32_32x32x16_bf16 v[48:63], v[244:247], v[198:201], v[48:63]
	ds_read_b128 v[244:247], v176 offset:26624
	s_waitcnt lgkmcnt(3)
	v_mfma_f32_32x32x16_bf16 v[32:47], v[248:251], v[198:201], v[32:47]
	ds_read_b128 v[248:251], v176 offset:27136
	s_waitcnt lgkmcnt(3)
	v_mfma_f32_32x32x16_bf16 v[48:63], v[214:217], v[202:205], v[48:63]
	ds_read_b128 v[214:217], v176 offset:3072
	s_waitcnt lgkmcnt(3)
	v_mfma_f32_32x32x16_bf16 v[32:47], v[218:221], v[202:205], v[32:47]
	ds_read_b128 v[218:221], v176 offset:11264
	s_waitcnt lgkmcnt(3)
	v_mfma_f32_32x32x16_bf16 v[48:63], v[244:247], v[206:209], v[48:63]
	ds_read_b128 v[244:247], v176 offset:19456
	s_waitcnt lgkmcnt(3)
	v_mfma_f32_32x32x16_bf16 v[32:47], v[248:251], v[206:209], v[32:47]
	ds_read_b128 v[248:251], v176 offset:27648
	s_waitcnt lgkmcnt(3)
	v_mfma_f32_32x32x16_bf16 v[16:31], v[214:217], v[194:197], 0
	ds_read_b128 v[214:217], v176 offset:3584
	s_waitcnt lgkmcnt(3)
	v_mfma_f32_32x32x16_bf16 v[16:31], v[218:221], v[198:201], v[16:31]
	ds_read_b128 v[218:221], v176 offset:11776
	s_waitcnt lgkmcnt(3)
	v_mfma_f32_32x32x16_bf16 v[16:31], v[244:247], v[202:205], v[16:31]
	ds_read_b128 v[244:247], v176 offset:19968
	s_waitcnt lgkmcnt(3)
	v_mfma_f32_32x32x16_bf16 v[16:31], v[248:251], v[206:209], v[16:31]
	ds_read_b128 v[222:225], v176 offset:28160
	s_waitcnt lgkmcnt(3)
	v_mfma_f32_32x32x16_bf16 v[0:15], v[214:217], v[194:197], 0
	s_waitcnt lgkmcnt(2)
	v_mfma_f32_32x32x16_bf16 v[0:15], v[218:221], v[198:201], v[0:15]
	s_waitcnt lgkmcnt(1)
	v_mfma_f32_32x32x16_bf16 v[0:15], v[244:247], v[202:205], v[0:15]
	s_waitcnt vmcnt(3)
	ds_write_b128 v210, v[226:229] offset:32768
	s_waitcnt vmcnt(2)
	ds_write_b128 v210, v[230:233] offset:33792
	s_waitcnt vmcnt(1)
	ds_write_b128 v210, v[234:237] offset:34816
	s_waitcnt vmcnt(0)
	ds_write_b128 v210, v[238:241] offset:35840
	s_waitcnt lgkmcnt(0)
	s_barrier
; #define XLAS __attribute__((address_space(3)))
; #define X_LOADK(dc) do { _Pragma("unroll") for (int i_ = 0; i_ < 4; ++i_) st[i_] = *(const u32x4*)(Kg + (dc) * 64 + (size_t)i_ * 64 * 1024); } while (0)
; #define X_LOADV(c)  do { _Pragma("unroll") for (int i_ = 0; i_ < 4; ++i_) st[i_] = *(const u32x4*)(Vg + (size_t)(c) * 64 * 2048 + i_ * 64); } while (0)
; #define X_STOREK(buf) do { _Pragma("unroll") for (int i_ = 0; i_ < 4; ++i_) *(XLAS u32x4*)(lds + (buf) + wid * 4096 + (64 * i_ + lane) * 16) = st[i_]; } while (0)
; #define X_STOREV(buf) do { _Pragma("unroll") for (int i_ = 0; i_ < 4; ++i_) *(XLAS u32x4*)(lds + (buf) + (wid + 8 * i_) * 1024 + lane * 16) = st[i_]; } while (0)
; __device__ __forceinline__ void unit(int b, int h, int qblk, const bf16_t* __restrict__ CQ, const bf16_t* __restrict__ CK, const bf16_t* __restrict__ CVT, bf16_t* __restrict__ CO, XLAS unsigned char* lds, const int wv) {
;     ...
; #pragma unroll
;     for (int dc = 0; dc < 4; ++dc) {
;         const int buf = (dc & 1) ? XB1 : XB0, nbuf = (dc & 1) ? XB0 : XB1;
;         if (dc < 3) X_LOADK(dc + 1); else X_LOADV(0);
; #pragma unroll
;         for (int kt = 0; kt < 8; ++kt)
; #pragma unroll
;             for (int ks = 0; ks < 4; ++ks) {
;                 const bf16x8 kf = *(const XLAS bf16x8*)(lds + buf + koff + kt * 512 + ks * 8192);
;                 s[kt] = __builtin_amdgcn_mfma_f32_32x32x16_bf16(kf, qfa[dc][ks], s[kt], 0, 0, 0);
;             }
;         if (dc < 3) X_STOREK(nbuf); else X_STOREV(nbuf);
;         __syncthreads();
;     }
	global_load_dwordx4 v[226:229], v[180:181], off offset:256
	global_load_dwordx4 v[230:233], v[182:183], off offset:256
	global_load_dwordx4 v[234:237], v[184:185], off offset:256
	global_load_dwordx4 v[238:241], v[186:187], off offset:256
	ds_read_b128 v[194:197], v176 offset:32768
	ds_read_b128 v[198:201], v176 offset:40960
	ds_read_b128 v[202:205], v176 offset:49152
	ds_read_b128 v[244:247], v176 offset:57344
	ds_read_b128 v[248:251], v176 offset:33280
	s_waitcnt lgkmcnt(4)
	v_mfma_f32_32x32x16_bf16 v[112:127], v[194:197], v[172:175], v[112:127]
	ds_read_b128 v[194:197], v176 offset:33792
	s_waitcnt lgkmcnt(4)
	v_mfma_f32_32x32x16_bf16 v[112:127], v[198:201], v[168:171], v[112:127]
	v_mfma_f32_32x32x16_bf16 v[0:15], v[222:225], v[206:209], v[0:15]
	ds_read_b128 v[198:201], v176 offset:41472
	s_waitcnt lgkmcnt(4)
	v_mfma_f32_32x32x16_bf16 v[112:127], v[202:205], v[164:167], v[112:127]
	ds_read_b128 v[202:205], v176 offset:41984
	s_waitcnt lgkmcnt(4)
	v_mfma_f32_32x32x16_bf16 v[112:127], v[244:247], v[160:163], v[112:127]
	ds_read_b128 v[244:247], v176 offset:49664
	s_waitcnt lgkmcnt(4)
	v_mfma_f32_32x32x16_bf16 v[96:111], v[248:251], v[172:175], v[96:111]
	ds_read_b128 v[248:251], v176 offset:50176
	s_waitcnt lgkmcnt(4)
	v_mfma_f32_32x32x16_bf16 v[80:95], v[194:197], v[172:175], v[80:95]
	ds_read_b128 v[194:197], v176 offset:57856
	s_waitcnt lgkmcnt(4)
	v_mfma_f32_32x32x16_bf16 v[96:111], v[198:201], v[168:171], v[96:111]
	ds_read_b128 v[198:201], v176 offset:58368
	s_waitcnt lgkmcnt(4)
	v_mfma_f32_32x32x16_bf16 v[80:95], v[202:205], v[168:171], v[80:95]
	ds_read_b128 v[202:205], v176 offset:34304
	s_waitcnt lgkmcnt(4)
	v_mfma_f32_32x32x16_bf16 v[96:111], v[244:247], v[164:167], v[96:111]
	ds_read_b128 v[244:247], v176 offset:34816
	s_waitcnt lgkmcnt(4)
	v_mfma_f32_32x32x16_bf16 v[80:95], v[248:251], v[164:167], v[80:95]
	ds_read_b128 v[248:251], v176 offset:42496
	s_waitcnt lgkmcnt(4)
	v_mfma_f32_32x32x16_bf16 v[96:111], v[194:197], v[160:163], v[96:111]
	ds_read_b128 v[194:197], v176 offset:43008
	s_waitcnt lgkmcnt(4)
	v_mfma_f32_32x32x16_bf16 v[80:95], v[198:201], v[160:163], v[80:95]
	ds_read_b128 v[198:201], v176 offset:50688
	s_waitcnt lgkmcnt(4)
	v_mfma_f32_32x32x16_bf16 v[64:79], v[202:205], v[172:175], v[64:79]
	ds_read_b128 v[202:205], v176 offset:51200
	s_waitcnt lgkmcnt(4)
	v_mfma_f32_32x32x16_bf16 v[48:63], v[244:247], v[172:175], v[48:63]
	ds_read_b128 v[244:247], v176 offset:58880
	s_waitcnt lgkmcnt(4)
	v_mfma_f32_32x32x16_bf16 v[64:79], v[248:251], v[168:171], v[64:79]
	ds_read_b128 v[248:251], v176 offset:59392
	s_waitcnt lgkmcnt(4)
	v_mfma_f32_32x32x16_bf16 v[48:63], v[194:197], v[168:171], v[48:63]
	ds_read_b128 v[194:197], v176 offset:35328
	s_waitcnt lgkmcnt(4)
	v_mfma_f32_32x32x16_bf16 v[64:79], v[198:201], v[164:167], v[64:79]
	ds_read_b128 v[198:201], v176 offset:35840
	s_waitcnt lgkmcnt(4)
	v_mfma_f32_32x32x16_bf16 v[48:63], v[202:205], v[164:167], v[48:63]
	ds_read_b128 v[202:205], v176 offset:43520
	s_waitcnt lgkmcnt(4)
	v_mfma_f32_32x32x16_bf16 v[64:79], v[244:247], v[160:163], v[64:79]
	ds_read_b128 v[244:247], v176 offset:44032
	s_waitcnt lgkmcnt(4)
	v_mfma_f32_32x32x16_bf16 v[48:63], v[248:251], v[160:163], v[48:63]
	ds_read_b128 v[248:251], v176 offset:51712
	s_waitcnt lgkmcnt(4)
	v_mfma_f32_32x32x16_bf16 v[32:47], v[194:197], v[172:175], v[32:47]
	ds_read_b128 v[194:197], v176 offset:52224
	s_waitcnt lgkmcnt(4)
	v_mfma_f32_32x32x16_bf16 v[16:31], v[198:201], v[172:175], v[16:31]
	ds_read_b128 v[198:201], v176 offset:36352
	s_waitcnt lgkmcnt(4)
	v_mfma_f32_32x32x16_bf16 v[32:47], v[202:205], v[168:171], v[32:47]
	ds_read_b128 v[202:205], v176 offset:59904
	s_waitcnt lgkmcnt(4)
	v_mfma_f32_32x32x16_bf16 v[16:31], v[244:247], v[168:171], v[16:31]
	ds_read_b128 v[244:247], v176 offset:60416
	s_waitcnt lgkmcnt(4)
	v_mfma_f32_32x32x16_bf16 v[32:47], v[248:251], v[164:167], v[32:47]
	ds_read_b128 v[248:251], v176 offset:44544
	s_waitcnt lgkmcnt(4)
	v_mfma_f32_32x32x16_bf16 v[16:31], v[194:197], v[164:167], v[16:31]
	ds_read_b128 v[206:209], v176 offset:52736
	s_waitcnt lgkmcnt(4)
	v_mfma_f32_32x32x16_bf16 v[0:15], v[198:201], v[172:175], v[0:15]
	s_waitcnt lgkmcnt(3)
	v_mfma_f32_32x32x16_bf16 v[32:47], v[202:205], v[160:163], v[32:47]
	ds_read_b128 v[214:217], v176 offset:60928
	s_waitcnt lgkmcnt(3)
	v_mfma_f32_32x32x16_bf16 v[16:31], v[244:247], v[160:163], v[16:31]
	s_waitcnt lgkmcnt(2)
	v_mfma_f32_32x32x16_bf16 v[0:15], v[248:251], v[168:171], v[0:15]
	s_waitcnt vmcnt(3)
	ds_write_b128 v210, v[226:229]
	s_waitcnt vmcnt(2)
	ds_write_b128 v210, v[230:233] offset:1024
	s_waitcnt vmcnt(1)
	ds_write_b128 v210, v[234:237] offset:2048
	s_waitcnt vmcnt(0)
	ds_write_b128 v210, v[238:241] offset:3072
	v_mfma_f32_32x32x16_bf16 v[0:15], v[206:209], v[164:167], v[0:15]
	s_waitcnt lgkmcnt(0)
	s_barrier
; #define XLAS __attribute__((address_space(3)))
; #define X_LOADK(dc) do { _Pragma("unroll") for (int i_ = 0; i_ < 4; ++i_) st[i_] = *(const u32x4*)(Kg + (dc) * 64 + (size_t)i_ * 64 * 1024); } while (0)
; #define X_LOADV(c)  do { _Pragma("unroll") for (int i_ = 0; i_ < 4; ++i_) st[i_] = *(const u32x4*)(Vg + (size_t)(c) * 64 * 2048 + i_ * 64); } while (0)
; #define X_STOREK(buf) do { _Pragma("unroll") for (int i_ = 0; i_ < 4; ++i_) *(XLAS u32x4*)(lds + (buf) + wid * 4096 + (64 * i_ + lane) * 16) = st[i_]; } while (0)
; #define X_STOREV(buf) do { _Pragma("unroll") for (int i_ = 0; i_ < 4; ++i_) *(XLAS u32x4*)(lds + (buf) + (wid + 8 * i_) * 1024 + lane * 16) = st[i_]; } while (0)
; __device__ __forceinline__ void unit(int b, int h, int qblk, const bf16_t* __restrict__ CQ, const bf16_t* __restrict__ CK, const bf16_t* __restrict__ CVT, bf16_t* __restrict__ CO, XLAS unsigned char* lds, const int wv) {
;     ...
; #pragma unroll
;     for (int dc = 0; dc < 4; ++dc) {
;         const int buf = (dc & 1) ? XB1 : XB0, nbuf = (dc & 1) ? XB0 : XB1;
;         if (dc < 3) X_LOADK(dc + 1); else X_LOADV(0);
; #pragma unroll
;         for (int kt = 0; kt < 8; ++kt)
; #pragma unroll
;             for (int ks = 0; ks < 4; ++ks) {
;                 const bf16x8 kf = *(const XLAS bf16x8*)(lds + buf + koff + kt * 512 + ks * 8192);
;                 s[kt] = __builtin_amdgcn_mfma_f32_32x32x16_bf16(kf, qfa[dc][ks], s[kt], 0, 0, 0);
;             }
;         if (dc < 3) X_STOREK(nbuf); else X_STOREV(nbuf);
;         __syncthreads();
;     }
	global_load_dwordx4 v[226:229], v[180:181], off offset:384
	global_load_dwordx4 v[230:233], v[182:183], off offset:384
	global_load_dwordx4 v[234:237], v[184:185], off offset:384
	global_load_dwordx4 v[238:241], v[186:187], off offset:384
	v_mfma_f32_32x32x16_bf16 v[0:15], v[214:217], v[160:163], v[0:15]
	ds_read_b128 v[160:163], v176
	ds_read_b128 v[164:167], v176 offset:8192
	ds_read_b128 v[168:171], v176 offset:16384
	ds_read_b128 v[244:247], v176 offset:24576
	ds_read_b128 v[248:251], v176 offset:512
	s_waitcnt lgkmcnt(4)
	v_mfma_f32_32x32x16_bf16 v[112:127], v[160:163], v[156:159], v[112:127]
	ds_read_b128 v[160:163], v176 offset:1024
	s_waitcnt lgkmcnt(4)
	v_mfma_f32_32x32x16_bf16 v[112:127], v[164:167], v[152:155], v[112:127]
	ds_read_b128 v[164:167], v176 offset:8704
	s_waitcnt lgkmcnt(4)
	v_mfma_f32_32x32x16_bf16 v[112:127], v[168:171], v[148:151], v[112:127]
	ds_read_b128 v[168:171], v176 offset:9216
	s_waitcnt lgkmcnt(4)
	v_mfma_f32_32x32x16_bf16 v[112:127], v[244:247], v[144:147], v[112:127]
	ds_read_b128 v[244:247], v176 offset:16896
	s_waitcnt lgkmcnt(4)
	v_mfma_f32_32x32x16_bf16 v[96:111], v[248:251], v[156:159], v[96:111]
	ds_read_b128 v[248:251], v176 offset:17408
	s_waitcnt lgkmcnt(4)
	v_mfma_f32_32x32x16_bf16 v[80:95], v[160:163], v[156:159], v[80:95]
	ds_read_b128 v[160:163], v176 offset:25088
	s_waitcnt lgkmcnt(4)
	v_mfma_f32_32x32x16_bf16 v[96:111], v[164:167], v[152:155], v[96:111]
	ds_read_b128 v[164:167], v176 offset:25600
	s_waitcnt lgkmcnt(4)
	v_mfma_f32_32x32x16_bf16 v[80:95], v[168:171], v[152:155], v[80:95]
	ds_read_b128 v[168:171], v176 offset:1536
	s_waitcnt lgkmcnt(4)
	v_mfma_f32_32x32x16_bf16 v[96:111], v[244:247], v[148:151], v[96:111]
	ds_read_b128 v[244:247], v176 offset:2048
	s_waitcnt lgkmcnt(4)
	v_mfma_f32_32x32x16_bf16 v[80:95], v[248:251], v[148:151], v[80:95]
	ds_read_b128 v[248:251], v176 offset:9728
	s_waitcnt lgkmcnt(4)
	v_mfma_f32_32x32x16_bf16 v[96:111], v[160:163], v[144:147], v[96:111]
	ds_read_b128 v[160:163], v176 offset:10240
	s_waitcnt lgkmcnt(4)
	v_mfma_f32_32x32x16_bf16 v[80:95], v[164:167], v[144:147], v[80:95]
	ds_read_b128 v[164:167], v176 offset:17920
	s_waitcnt lgkmcnt(4)
	v_mfma_f32_32x32x16_bf16 v[64:79], v[168:171], v[156:159], v[64:79]
	ds_read_b128 v[168:171], v176 offset:18432
	s_waitcnt lgkmcnt(4)
	v_mfma_f32_32x32x16_bf16 v[48:63], v[244:247], v[156:159], v[48:63]
	ds_read_b128 v[244:247], v176 offset:26112
	s_waitcnt lgkmcnt(4)
	v_mfma_f32_32x32x16_bf16 v[64:79], v[248:251], v[152:155], v[64:79]
	ds_read_b128 v[248:251], v176 offset:26624
	s_waitcnt lgkmcnt(4)
	v_mfma_f32_32x32x16_bf16 v[48:63], v[160:163], v[152:155], v[48:63]
	ds_read_b128 v[160:163], v176 offset:2560
	s_waitcnt lgkmcnt(4)
	v_mfma_f32_32x32x16_bf16 v[64:79], v[164:167], v[148:151], v[64:79]
	ds_read_b128 v[164:167], v176 offset:3072
	s_waitcnt lgkmcnt(4)
	v_mfma_f32_32x32x16_bf16 v[48:63], v[168:171], v[148:151], v[48:63]
	ds_read_b128 v[168:171], v176 offset:10752
	s_waitcnt lgkmcnt(4)
	v_mfma_f32_32x32x16_bf16 v[64:79], v[244:247], v[144:147], v[64:79]
	ds_read_b128 v[244:247], v176 offset:11264
	s_waitcnt lgkmcnt(4)
	v_mfma_f32_32x32x16_bf16 v[48:63], v[248:251], v[144:147], v[48:63]
	ds_read_b128 v[248:251], v176 offset:18944
	s_waitcnt lgkmcnt(4)
	v_mfma_f32_32x32x16_bf16 v[32:47], v[160:163], v[156:159], v[32:47]
	ds_read_b128 v[160:163], v176 offset:19456
	s_waitcnt lgkmcnt(4)
	v_mfma_f32_32x32x16_bf16 v[16:31], v[164:167], v[156:159], v[16:31]
	ds_read_b128 v[164:167], v176 offset:3584
	s_waitcnt lgkmcnt(4)
	v_mfma_f32_32x32x16_bf16 v[32:47], v[168:171], v[152:155], v[32:47]
	ds_read_b128 v[168:171], v176 offset:27136
	s_waitcnt lgkmcnt(4)
	v_mfma_f32_32x32x16_bf16 v[16:31], v[244:247], v[152:155], v[16:31]
	ds_read_b128 v[244:247], v176 offset:27648
	s_waitcnt lgkmcnt(4)
	v_mfma_f32_32x32x16_bf16 v[32:47], v[248:251], v[148:151], v[32:47]
	ds_read_b128 v[248:251], v176 offset:11776
	s_waitcnt lgkmcnt(4)
	v_mfma_f32_32x32x16_bf16 v[16:31], v[160:163], v[148:151], v[16:31]
	ds_read_b128 v[172:175], v176 offset:19968
	s_waitcnt lgkmcnt(4)
	v_mfma_f32_32x32x16_bf16 v[0:15], v[164:167], v[156:159], v[0:15]
	s_waitcnt lgkmcnt(3)
	v_mfma_f32_32x32x16_bf16 v[32:47], v[168:171], v[144:147], v[32:47]
	ds_read_b128 v[194:197], v176 offset:28160
	s_waitcnt lgkmcnt(3)
	v_mfma_f32_32x32x16_bf16 v[16:31], v[244:247], v[144:147], v[16:31]
	s_waitcnt lgkmcnt(2)
	v_mfma_f32_32x32x16_bf16 v[0:15], v[248:251], v[152:155], v[0:15]
	s_waitcnt vmcnt(3)
	ds_write_b128 v210, v[226:229] offset:32768
	s_waitcnt vmcnt(2)
	ds_write_b128 v210, v[230:233] offset:33792
	s_waitcnt vmcnt(1)
	ds_write_b128 v210, v[234:237] offset:34816
	s_waitcnt vmcnt(0)
	ds_write_b128 v210, v[238:241] offset:35840
	v_mfma_f32_32x32x16_bf16 v[0:15], v[172:175], v[148:151], v[0:15]
	s_waitcnt lgkmcnt(0)
	s_barrier
; #define XLAS __attribute__((address_space(3)))
; #define X_LOADK(dc) do { _Pragma("unroll") for (int i_ = 0; i_ < 4; ++i_) st[i_] = *(const u32x4*)(Kg + (dc) * 64 + (size_t)i_ * 64 * 1024); } while (0)
; #define X_LOADV(c)  do { _Pragma("unroll") for (int i_ = 0; i_ < 4; ++i_) st[i_] = *(const u32x4*)(Vg + (size_t)(c) * 64 * 2048 + i_ * 64); } while (0)
; #define X_STOREK(buf) do { _Pragma("unroll") for (int i_ = 0; i_ < 4; ++i_) *(XLAS u32x4*)(lds + (buf) + wid * 4096 + (64 * i_ + lane) * 16) = st[i_]; } while (0)
; #define X_STOREV(buf) do { _Pragma("unroll") for (int i_ = 0; i_ < 4; ++i_) *(XLAS u32x4*)(lds + (buf) + (wid + 8 * i_) * 1024 + lane * 16) = st[i_]; } while (0)
; __device__ __forceinline__ void unit(int b, int h, int qblk, const bf16_t* __restrict__ CQ, const bf16_t* __restrict__ CK, const bf16_t* __restrict__ CVT, bf16_t* __restrict__ CO, XLAS unsigned char* lds, const int wv) {
;     ...
; #pragma unroll
;     for (int dc = 0; dc < 4; ++dc) {
;         const int buf = (dc & 1) ? XB1 : XB0, nbuf = (dc & 1) ? XB0 : XB1;
;         if (dc < 3) X_LOADK(dc + 1); else X_LOADV(0);
; #pragma unroll
;         for (int kt = 0; kt < 8; ++kt)
; #pragma unroll
;             for (int ks = 0; ks < 4; ++ks) {
;                 const bf16x8 kf = *(const XLAS bf16x8*)(lds + buf + koff + kt * 512 + ks * 8192);
;                 s[kt] = __builtin_amdgcn_mfma_f32_32x32x16_bf16(kf, qfa[dc][ks], s[kt], 0, 0, 0);
;             }
;         if (dc < 3) X_STOREK(nbuf); else X_STOREV(nbuf);
;         __syncthreads();
;     }
;     float mx = s[0][0];
; #pragma unroll
;     for (int kt = 0; kt < 8; ++kt)
; #pragma unroll
;         for (int r = 0; r < 16; ++r) mx = fmaxf(mx, s[kt][r]);
	v_lshl_add_u64 v[242:243], v[178:179], 0, s[14:15]
	v_lshl_add_u64 v[242:243], v[242:243], 0, s[16:17]
	global_load_dwordx4 v[226:229], v[242:243], off
	global_load_dwordx4 v[230:233], v[242:243], off offset:128
	global_load_dwordx4 v[234:237], v[242:243], off offset:256
	global_load_dwordx4 v[238:241], v[242:243], off offset:384
	v_mfma_f32_32x32x16_bf16 v[0:15], v[194:197], v[144:147], v[0:15]
	ds_read_b128 v[144:147], v176 offset:32768
	ds_read_b128 v[160:163], v176 offset:40960
	ds_read_b128 v[244:247], v176 offset:49152
	ds_read_b128 v[248:251], v176 offset:57344
	ds_read_b128 v[164:167], v176 offset:33280
	s_waitcnt lgkmcnt(4)
	v_mfma_f32_32x32x16_bf16 v[112:127], v[144:147], v[140:143], v[112:127]
	ds_read_b128 v[168:171], v176 offset:33792
	s_waitcnt lgkmcnt(4)
	v_mfma_f32_32x32x16_bf16 v[112:127], v[160:163], v[136:139], v[112:127]
	ds_read_b128 v[144:147], v176 offset:41472
	s_waitcnt lgkmcnt(4)
	v_mfma_f32_32x32x16_bf16 v[112:127], v[244:247], v[132:135], v[112:127]
	ds_read_b128 v[160:163], v176 offset:41984
	s_waitcnt lgkmcnt(4)
	v_mfma_f32_32x32x16_bf16 v[112:127], v[248:251], v[128:131], v[112:127]
	ds_read_b128 v[244:247], v176 offset:49664
	s_waitcnt lgkmcnt(4)
	v_mfma_f32_32x32x16_bf16 v[96:111], v[164:167], v[140:143], v[96:111]
	ds_read_b128 v[248:251], v176 offset:50176
	s_waitcnt lgkmcnt(4)
	v_mfma_f32_32x32x16_bf16 v[80:95], v[168:171], v[140:143], v[80:95]
	ds_read_b128 v[164:167], v176 offset:57856
	s_waitcnt lgkmcnt(4)
	v_mfma_f32_32x32x16_bf16 v[96:111], v[144:147], v[136:139], v[96:111]
	ds_read_b128 v[168:171], v176 offset:58368
	s_waitcnt lgkmcnt(4)
	v_mfma_f32_32x32x16_bf16 v[80:95], v[160:163], v[136:139], v[80:95]
	ds_read_b128 v[144:147], v176 offset:34304
	s_waitcnt lgkmcnt(4)
	v_mfma_f32_32x32x16_bf16 v[96:111], v[244:247], v[132:135], v[96:111]
	ds_read_b128 v[160:163], v176 offset:34816
	s_waitcnt lgkmcnt(4)
	v_mfma_f32_32x32x16_bf16 v[80:95], v[248:251], v[132:135], v[80:95]
	ds_read_b128 v[244:247], v176 offset:42496
	s_waitcnt lgkmcnt(4)
	v_mfma_f32_32x32x16_bf16 v[96:111], v[164:167], v[128:131], v[96:111]
	ds_read_b128 v[248:251], v176 offset:43008
	s_waitcnt lgkmcnt(4)
	v_mfma_f32_32x32x16_bf16 v[80:95], v[168:171], v[128:131], v[80:95]
	ds_read_b128 v[164:167], v176 offset:50688
	s_waitcnt lgkmcnt(4)
	v_mfma_f32_32x32x16_bf16 v[64:79], v[144:147], v[140:143], v[64:79]
	ds_read_b128 v[168:171], v176 offset:51200
	s_waitcnt lgkmcnt(4)
	v_mfma_f32_32x32x16_bf16 v[48:63], v[160:163], v[140:143], v[48:63]
	ds_read_b128 v[144:147], v176 offset:58880
	s_waitcnt lgkmcnt(4)
	v_mfma_f32_32x32x16_bf16 v[64:79], v[244:247], v[136:139], v[64:79]
	ds_read_b128 v[148:151], v176 offset:35328
	s_waitcnt lgkmcnt(4)
	v_mfma_f32_32x32x16_bf16 v[48:63], v[248:251], v[136:139], v[48:63]
	ds_read_b128 v[152:155], v176 offset:43520
	s_waitcnt lgkmcnt(4)
	v_mfma_f32_32x32x16_bf16 v[64:79], v[164:167], v[132:135], v[64:79]
	ds_read_b128 v[156:159], v176 offset:51712
	s_waitcnt lgkmcnt(4)
	v_mfma_f32_32x32x16_bf16 v[48:63], v[168:171], v[132:135], v[48:63]
	s_waitcnt lgkmcnt(3)
	v_mfma_f32_32x32x16_bf16 v[64:79], v[144:147], v[128:131], v[64:79]
	ds_read_b128 v[144:147], v176 offset:59392
	ds_read_b128 v[160:163], v176 offset:59904
	s_waitcnt lgkmcnt(1)
	v_mfma_f32_32x32x16_bf16 v[48:63], v[144:147], v[128:131], v[48:63]
	v_lshl_add_u64 v[144:145], v[178:179], 0, s[14:15]
	v_lshl_add_u64 v[144:145], v[144:145], 0, s[16:17]
	s_lshl_b32 s14, s29, 10
	s_add_i32 s14, s14, 0
	v_add_u32_e32 v146, s14, v193
	v_max_f32_e32 v147, v113, v113
	v_mfma_f32_32x32x16_bf16 v[32:47], v[148:151], v[140:143], v[32:47]
	s_and_b32 s14, s27, 0x3fffffc0
	s_lshl_b32 s14, s14, 2
	s_add_i32 s17, s14, 0
	s_lshl_b32 s16, s28, 8
	s_add_i32 s17, s17, 0x10000
	v_mfma_f32_32x32x16_bf16 v[32:47], v[152:155], v[136:139], v[32:47]
	ds_read_b128 v[172:175], v176 offset:35840
	ds_read_b128 v[178:181], v176 offset:36352
	ds_read_b128 v[182:185], v176 offset:44032
	ds_read_b128 v[194:197], v176 offset:44544
	ds_read_b128 v[198:201], v176 offset:52224
	ds_read_b128 v[202:205], v176 offset:52736
	v_mfma_f32_32x32x16_bf16 v[32:47], v[156:159], v[132:135], v[32:47]
	ds_read_b128 v[156:159], v176 offset:60416
	ds_read_b128 v[206:209], v176 offset:60928
	s_waitcnt vmcnt(3)
	ds_write_b128 v146, v[226:229]
	s_waitcnt vmcnt(2)
	ds_write_b128 v146, v[230:233] offset:8192
	s_waitcnt vmcnt(1)
	ds_write_b128 v146, v[234:237] offset:16384
	v_max_f32_e32 v148, v112, v112
	v_max_f32_e32 v147, v148, v147
	v_max3_f32 v147, v147, v114, v115
	v_max3_f32 v147, v147, v116, v117
	v_max3_f32 v147, v147, v118, v119
	v_max3_f32 v147, v147, v120, v121
	v_max3_f32 v147, v147, v122, v123
	v_max3_f32 v147, v147, v124, v125
	v_max3_f32 v147, v147, v126, v127
	v_max3_f32 v147, v147, v96, v97
	v_max3_f32 v147, v147, v98, v99
	v_max3_f32 v147, v147, v100, v101
	v_max3_f32 v147, v147, v102, v103
	v_max3_f32 v147, v147, v104, v105
	v_max3_f32 v147, v147, v106, v107
	v_max3_f32 v147, v147, v108, v109
	v_max3_f32 v147, v147, v110, v111
	s_waitcnt lgkmcnt(10)
	v_mfma_f32_32x32x16_bf16 v[16:31], v[172:175], v[140:143], v[16:31]
	v_max3_f32 v147, v147, v80, v81
	v_max3_f32 v147, v147, v82, v83
	v_max3_f32 v147, v147, v84, v85
	v_max3_f32 v147, v147, v86, v87
	v_max3_f32 v147, v147, v88, v89
	v_max3_f32 v147, v147, v90, v91
	v_max3_f32 v147, v147, v92, v93
	v_max3_f32 v147, v147, v94, v95
	s_waitcnt lgkmcnt(8)
	v_mfma_f32_32x32x16_bf16 v[16:31], v[182:185], v[136:139], v[16:31]
	v_max3_f32 v147, v147, v64, v65
	v_max3_f32 v147, v147, v66, v67
	v_max3_f32 v147, v147, v68, v69
	v_max3_f32 v147, v147, v70, v71
	v_max3_f32 v147, v147, v72, v73
	v_max3_f32 v147, v147, v74, v75
	v_max3_f32 v147, v147, v76, v77
	v_mfma_f32_32x32x16_bf16 v[0:15], v[178:181], v[140:143], v[0:15]
	v_max3_f32 v147, v147, v78, v79
	v_max3_f32 v147, v147, v48, v49
	v_max3_f32 v147, v147, v50, v51
	v_max3_f32 v147, v147, v52, v53
	v_max3_f32 v140, v147, v54, v55
	v_max3_f32 v140, v140, v56, v57
	v_max3_f32 v140, v140, v58, v59
	v_mfma_f32_32x32x16_bf16 v[32:47], v[160:163], v[128:131], v[32:47]
	v_max3_f32 v140, v140, v60, v61
	v_max3_f32 v140, v140, v62, v63
	s_waitcnt vmcnt(0)
	ds_write_b128 v146, v[238:241] offset:24576
	s_waitcnt lgkmcnt(0)
	s_barrier
; __device__ __forceinline__ void unit(int b, int h, int qblk, const bf16_t* __restrict__ CQ, const bf16_t* __restrict__ CK, const bf16_t* __restrict__ CVT, bf16_t* __restrict__ CO, XLAS unsigned char* lds, const int wv) {
;     ...
;     float mx = s[0][0];
; #pragma unroll
;     for (int kt = 0; kt < 8; ++kt)
; #pragma unroll
;         for (int r = 0; r < 16; ++r) mx = fmaxf(mx, s[kt][r]);
;     mx = fmaxf(mx, __shfl_xor(mx, 32));
;     float l = 0.f;
; #pragma unroll
;     for (int kt = 0; kt < 8; ++kt)
; #pragma unroll
;         for (int r = 0; r < 16; ++r) { const float p = __builtin_amdgcn_exp2f(s[kt][r] - mx); s[kt][r] = p; l += p; }
;     l += __shfl_xor(l, 32);
	s_nop 5
	v_max3_f32 v140, v140, v32, v33
	v_mfma_f32_32x32x16_bf16 v[16:31], v[198:201], v[132:135], v[16:31]
	v_max3_f32 v140, v140, v34, v35
	v_mfma_f32_32x32x16_bf16 v[0:15], v[194:197], v[136:139], v[0:15]
	v_max3_f32 v136, v140, v36, v37
	v_max3_f32 v136, v136, v38, v39
	v_max3_f32 v136, v136, v40, v41
	v_max3_f32 v136, v136, v42, v43
	v_max3_f32 v136, v136, v44, v45
	v_max3_f32 v136, v136, v46, v47
	v_mfma_f32_32x32x16_bf16 v[16:31], v[156:159], v[128:131], v[16:31]
	v_mfma_f32_32x32x16_bf16 v[0:15], v[202:205], v[132:135], v[0:15]
	s_nop 10
	v_max3_f32 v136, v136, v16, v17
	v_max3_f32 v132, v136, v18, v19
	v_max3_f32 v132, v132, v20, v21
	v_max3_f32 v132, v132, v22, v23
	v_max3_f32 v132, v132, v24, v25
	v_max3_f32 v132, v132, v26, v27
	v_max3_f32 v132, v132, v28, v29
	v_mfma_f32_32x32x16_bf16 v[0:15], v[206:209], v[128:131], v[0:15]
	v_max3_f32 v132, v132, v30, v31
	s_nop 10
	v_max3_f32 v128, v132, v0, v1
	v_max3_f32 v128, v128, v2, v3
	v_max3_f32 v128, v128, v4, v5
	v_max3_f32 v128, v128, v6, v7
	v_max3_f32 v128, v128, v8, v9
	v_max3_f32 v128, v128, v10, v11
	v_max3_f32 v128, v128, v12, v13
	v_max3_f32 v128, v128, v14, v15
	ds_bpermute_b32 v129, v188, v128
	s_waitcnt lgkmcnt(0)
	v_max_f32_e32 v129, v129, v129
	v_max_f32_e32 v128, v128, v129
	v_sub_f32_e32 v112, v112, v128
	v_exp_f32_e32 v112, v112
	v_sub_f32_e32 v113, v113, v128
	v_exp_f32_e32 v113, v113
	v_sub_f32_e32 v114, v114, v128
	v_exp_f32_e32 v114, v114
	v_sub_f32_e32 v115, v115, v128
	v_exp_f32_e32 v115, v115
	v_sub_f32_e32 v116, v116, v128
	v_add_f32_e32 v129, 0, v112
	v_exp_f32_e32 v116, v116
	v_sub_f32_e32 v117, v117, v128
	v_add_f32_e32 v129, v113, v129
	v_exp_f32_e32 v117, v117
	v_sub_f32_e32 v118, v118, v128
	v_add_f32_e32 v129, v114, v129
	v_exp_f32_e32 v118, v118
	v_sub_f32_e32 v119, v119, v128
	v_add_f32_e32 v129, v115, v129
	v_exp_f32_e32 v119, v119
	v_sub_f32_e32 v120, v120, v128
	v_add_f32_e32 v129, v116, v129
	v_exp_f32_e32 v120, v120
	v_sub_f32_e32 v121, v121, v128
	v_add_f32_e32 v129, v117, v129
	v_exp_f32_e32 v121, v121
	v_sub_f32_e32 v122, v122, v128
	v_add_f32_e32 v129, v118, v129
	v_exp_f32_e32 v122, v122
	v_sub_f32_e32 v123, v123, v128
	v_add_f32_e32 v129, v119, v129
	v_exp_f32_e32 v123, v123
	v_sub_f32_e32 v124, v124, v128
	v_add_f32_e32 v129, v120, v129
	v_exp_f32_e32 v124, v124
	v_sub_f32_e32 v125, v125, v128
	v_add_f32_e32 v129, v121, v129
	v_exp_f32_e32 v125, v125
	v_sub_f32_e32 v126, v126, v128
	v_add_f32_e32 v129, v122, v129
	v_exp_f32_e32 v126, v126
	v_sub_f32_e32 v127, v127, v128
	v_add_f32_e32 v129, v123, v129
	v_exp_f32_e32 v127, v127
	v_sub_f32_e32 v96, v96, v128
	v_add_f32_e32 v129, v124, v129
	v_exp_f32_e32 v96, v96
	v_sub_f32_e32 v97, v97, v128
	v_add_f32_e32 v129, v125, v129
	v_exp_f32_e32 v97, v97
	v_sub_f32_e32 v98, v98, v128
	v_add_f32_e32 v129, v126, v129
	v_exp_f32_e32 v98, v98
	v_sub_f32_e32 v99, v99, v128
	v_add_f32_e32 v129, v127, v129
	v_exp_f32_e32 v99, v99
	v_sub_f32_e32 v100, v100, v128
	v_add_f32_e32 v129, v96, v129
	v_exp_f32_e32 v100, v100
	v_sub_f32_e32 v101, v101, v128
	v_add_f32_e32 v129, v97, v129
	v_exp_f32_e32 v101, v101
	v_sub_f32_e32 v102, v102, v128
	v_add_f32_e32 v129, v98, v129
	v_exp_f32_e32 v102, v102
	v_sub_f32_e32 v103, v103, v128
	v_add_f32_e32 v129, v99, v129
	v_exp_f32_e32 v103, v103
	v_sub_f32_e32 v104, v104, v128
	v_add_f32_e32 v129, v100, v129
	v_exp_f32_e32 v104, v104
	v_sub_f32_e32 v105, v105, v128
	v_add_f32_e32 v129, v101, v129
	v_exp_f32_e32 v105, v105
	v_sub_f32_e32 v106, v106, v128
	v_add_f32_e32 v129, v102, v129
	v_exp_f32_e32 v106, v106
	v_sub_f32_e32 v107, v107, v128
	v_add_f32_e32 v129, v103, v129
	v_exp_f32_e32 v107, v107
	v_sub_f32_e32 v108, v108, v128
	v_add_f32_e32 v129, v104, v129
	v_exp_f32_e32 v108, v108
	v_sub_f32_e32 v109, v109, v128
	v_add_f32_e32 v129, v105, v129
	v_exp_f32_e32 v109, v109
	v_sub_f32_e32 v110, v110, v128
	v_add_f32_e32 v129, v106, v129
	v_exp_f32_e32 v110, v110
	v_sub_f32_e32 v111, v111, v128
	v_add_f32_e32 v129, v107, v129
	v_exp_f32_e32 v111, v111
	v_sub_f32_e32 v80, v80, v128
	v_add_f32_e32 v129, v108, v129
	v_exp_f32_e32 v130, v80
	v_sub_f32_e32 v80, v81, v128
	v_add_f32_e32 v129, v109, v129
	v_exp_f32_e32 v131, v80
	v_sub_f32_e32 v80, v82, v128
	v_add_f32_e32 v129, v110, v129
	v_exp_f32_e32 v132, v80
	v_sub_f32_e32 v80, v83, v128
	v_add_f32_e32 v129, v111, v129
	v_exp_f32_e32 v133, v80
	v_sub_f32_e32 v81, v84, v128
	v_add_f32_e32 v80, v130, v129
	v_exp_f32_e32 v129, v81
	v_sub_f32_e32 v81, v85, v128
	v_add_f32_e32 v80, v131, v80
	v_exp_f32_e32 v134, v81
	v_sub_f32_e32 v81, v86, v128
	v_add_f32_e32 v80, v132, v80
	v_exp_f32_e32 v135, v81
	v_sub_f32_e32 v81, v87, v128
	v_add_f32_e32 v80, v133, v80
	v_exp_f32_e32 v136, v81
	v_sub_f32_e32 v81, v88, v128
	v_add_f32_e32 v80, v129, v80
	v_exp_f32_e32 v137, v81
	v_sub_f32_e32 v81, v89, v128
	v_add_f32_e32 v80, v134, v80
	v_exp_f32_e32 v138, v81
	v_sub_f32_e32 v81, v90, v128
	v_add_f32_e32 v80, v135, v80
	v_exp_f32_e32 v139, v81
	v_sub_f32_e32 v81, v91, v128
	v_add_f32_e32 v80, v136, v80
	v_exp_f32_e32 v140, v81
	v_sub_f32_e32 v81, v92, v128
	v_add_f32_e32 v80, v137, v80
	v_exp_f32_e32 v141, v81
	v_sub_f32_e32 v81, v93, v128
	v_add_f32_e32 v80, v138, v80
	v_exp_f32_e32 v142, v81
	v_sub_f32_e32 v81, v94, v128
	v_add_f32_e32 v80, v139, v80
	v_exp_f32_e32 v143, v81
	v_sub_f32_e32 v81, v95, v128
	v_add_f32_e32 v80, v140, v80
	v_exp_f32_e32 v147, v81
	v_sub_f32_e32 v64, v64, v128
	v_add_f32_e32 v80, v141, v80
	v_exp_f32_e32 v64, v64
	v_sub_f32_e32 v65, v65, v128
	v_add_f32_e32 v80, v142, v80
	v_exp_f32_e32 v65, v65
	v_sub_f32_e32 v66, v66, v128
	v_add_f32_e32 v80, v143, v80
	v_exp_f32_e32 v66, v66
	v_sub_f32_e32 v67, v67, v128
; __device__ __forceinline__ void unit(int b, int h, int qblk, const bf16_t* __restrict__ CQ, const bf16_t* __restrict__ CK, const bf16_t* __restrict__ CVT, bf16_t* __restrict__ CO, XLAS unsigned char* lds, const int wv) {
;     ...
;     for (int kt = 0; kt < 8; ++kt)
; #pragma unroll
;         for (int r = 0; r < 16; ++r) { const float p = __builtin_amdgcn_exp2f(s[kt][r] - mx); s[kt][r] = p; l += p; }
	v_add_f32_e32 v80, v147, v80
	v_exp_f32_e32 v67, v67
	v_sub_f32_e32 v68, v68, v128
	v_add_f32_e32 v80, v64, v80
	v_exp_f32_e32 v148, v68
	v_sub_f32_e32 v68, v69, v128
	v_add_f32_e32 v80, v65, v80
	v_exp_f32_e32 v149, v68
	v_sub_f32_e32 v68, v70, v128
	v_add_f32_e32 v80, v66, v80
	v_exp_f32_e32 v150, v68
	v_sub_f32_e32 v68, v71, v128
	v_add_f32_e32 v80, v67, v80
	v_exp_f32_e32 v71, v68
	v_sub_f32_e32 v69, v72, v128
	v_add_f32_e32 v68, v148, v80
	v_exp_f32_e32 v151, v69
	v_sub_f32_e32 v69, v73, v128
	v_add_f32_e32 v68, v149, v68
	v_exp_f32_e32 v152, v69
	v_sub_f32_e32 v69, v74, v128
	v_add_f32_e32 v68, v150, v68
	v_exp_f32_e32 v153, v69
	v_sub_f32_e32 v69, v75, v128
	v_add_f32_e32 v68, v71, v68
	v_exp_f32_e32 v154, v69
	v_sub_f32_e32 v69, v76, v128
	v_add_f32_e32 v68, v151, v68
	v_exp_f32_e32 v155, v69
	v_sub_f32_e32 v69, v77, v128
	v_add_f32_e32 v68, v152, v68
	v_exp_f32_e32 v156, v69
	v_sub_f32_e32 v69, v78, v128
	v_add_f32_e32 v68, v153, v68
	v_exp_f32_e32 v157, v69
	v_sub_f32_e32 v69, v79, v128
	v_add_f32_e32 v68, v154, v68
	v_exp_f32_e32 v158, v69
	v_sub_f32_e32 v48, v48, v128
	v_add_f32_e32 v68, v155, v68
	v_exp_f32_e32 v48, v48
	v_sub_f32_e32 v49, v49, v128
	v_add_f32_e32 v68, v156, v68
	v_exp_f32_e32 v49, v49
	v_sub_f32_e32 v50, v50, v128
	v_add_f32_e32 v68, v157, v68
	v_exp_f32_e32 v50, v50
	v_sub_f32_e32 v51, v51, v128
	v_add_f32_e32 v68, v158, v68
	v_exp_f32_e32 v51, v51
	v_sub_f32_e32 v52, v52, v128
	v_add_f32_e32 v68, v48, v68
	v_exp_f32_e32 v52, v52
	v_sub_f32_e32 v53, v53, v128
	v_add_f32_e32 v68, v49, v68
	v_exp_f32_e32 v53, v53
	v_sub_f32_e32 v54, v54, v128
	v_add_f32_e32 v68, v50, v68
	v_exp_f32_e32 v54, v54
	v_sub_f32_e32 v55, v55, v128
	v_add_f32_e32 v68, v51, v68
	v_exp_f32_e32 v55, v55
	v_sub_f32_e32 v56, v56, v128
	v_add_f32_e32 v68, v52, v68
	v_exp_f32_e32 v56, v56
	v_sub_f32_e32 v57, v57, v128
	v_add_f32_e32 v68, v53, v68
	v_exp_f32_e32 v57, v57
	v_sub_f32_e32 v58, v58, v128
	v_add_f32_e32 v68, v54, v68
	v_exp_f32_e32 v58, v58
	v_sub_f32_e32 v59, v59, v128
	v_add_f32_e32 v68, v55, v68
	v_exp_f32_e32 v59, v59
	v_sub_f32_e32 v60, v60, v128
	v_add_f32_e32 v68, v56, v68
	v_exp_f32_e32 v159, v60
	v_sub_f32_e32 v60, v61, v128
	v_add_f32_e32 v68, v57, v68
	v_exp_f32_e32 v160, v60
	v_sub_f32_e32 v60, v62, v128
	v_add_f32_e32 v68, v58, v68
	v_exp_f32_e32 v161, v60
	v_sub_f32_e32 v60, v63, v128
	v_add_f32_e32 v68, v59, v68
	v_exp_f32_e32 v162, v60
	v_sub_f32_e32 v32, v32, v128
	v_add_f32_e32 v60, v159, v68
	v_exp_f32_e32 v32, v32
	v_sub_f32_e32 v33, v33, v128
	v_add_f32_e32 v60, v160, v60
	v_exp_f32_e32 v33, v33
	v_sub_f32_e32 v34, v34, v128
	v_add_f32_e32 v60, v161, v60
	v_exp_f32_e32 v34, v34
	v_sub_f32_e32 v35, v35, v128
	v_add_f32_e32 v60, v162, v60
	v_exp_f32_e32 v35, v35
	v_sub_f32_e32 v36, v36, v128
	v_add_f32_e32 v60, v32, v60
	v_exp_f32_e32 v36, v36
	v_sub_f32_e32 v37, v37, v128
	v_add_f32_e32 v60, v33, v60
	v_exp_f32_e32 v37, v37
	v_sub_f32_e32 v38, v38, v128
	v_add_f32_e32 v60, v34, v60
	v_exp_f32_e32 v38, v38
	v_sub_f32_e32 v39, v39, v128
	v_add_f32_e32 v60, v35, v60
	v_exp_f32_e32 v39, v39
	v_sub_f32_e32 v40, v40, v128
	v_add_f32_e32 v60, v36, v60
	v_exp_f32_e32 v40, v40
	v_sub_f32_e32 v41, v41, v128
	v_add_f32_e32 v60, v37, v60
	v_exp_f32_e32 v41, v41
	v_sub_f32_e32 v42, v42, v128
	v_add_f32_e32 v60, v38, v60
	v_exp_f32_e32 v42, v42
	v_sub_f32_e32 v43, v43, v128
	v_add_f32_e32 v60, v39, v60
	v_exp_f32_e32 v43, v43
	v_sub_f32_e32 v44, v44, v128
	v_add_f32_e32 v60, v40, v60
	v_exp_f32_e32 v44, v44
	v_sub_f32_e32 v45, v45, v128
	v_add_f32_e32 v60, v41, v60
	v_exp_f32_e32 v45, v45
	v_sub_f32_e32 v46, v46, v128
	v_add_f32_e32 v60, v42, v60
	v_exp_f32_e32 v46, v46
	v_sub_f32_e32 v47, v47, v128
	v_add_f32_e32 v60, v43, v60
	v_exp_f32_e32 v47, v47
	v_sub_f32_e32 v16, v16, v128
	v_add_f32_e32 v60, v44, v60
	v_exp_f32_e32 v16, v16
	v_sub_f32_e32 v17, v17, v128
	v_add_f32_e32 v60, v45, v60
	v_exp_f32_e32 v17, v17
	v_sub_f32_e32 v18, v18, v128
	v_add_f32_e32 v60, v46, v60
	v_exp_f32_e32 v18, v18
	v_sub_f32_e32 v19, v19, v128
	v_add_f32_e32 v60, v47, v60
	v_exp_f32_e32 v19, v19
	v_sub_f32_e32 v20, v20, v128
	v_add_f32_e32 v60, v16, v60
	v_exp_f32_e32 v20, v20
	v_sub_f32_e32 v21, v21, v128
	v_add_f32_e32 v60, v17, v60
	v_exp_f32_e32 v21, v21
	v_sub_f32_e32 v22, v22, v128
	v_add_f32_e32 v60, v18, v60
	v_exp_f32_e32 v22, v22
	v_sub_f32_e32 v23, v23, v128
	v_add_f32_e32 v60, v19, v60
	v_exp_f32_e32 v23, v23
; #define XLAS __attribute__((address_space(3)))
; __device__ __forceinline__ unsigned pk(float lo, float hi) { return pg8::cvt_pk_bf16(lo, hi); }
; __device__ __forceinline__ void unit(int b, int h, int qblk, const bf16_t* __restrict__ CQ, const bf16_t* __restrict__ CK, const bf16_t* __restrict__ CVT, bf16_t* __restrict__ CO, XLAS unsigned char* lds, const int wv) {
;     ...
;     for (int kt = 0; kt < 8; ++kt)
; #pragma unroll
;         for (int r = 0; r < 16; ++r) { const float p = __builtin_amdgcn_exp2f(s[kt][r] - mx); s[kt][r] = p; l += p; }
;     l += __shfl_xor(l, 32);
;     u32x4 pw[16];
; #pragma unroll
;     for (int kt = 0; kt < 8; ++kt)
; #pragma unroll
;         for (int j2 = 0; j2 < 2; ++j2)
;             pw[2 * kt + j2] = (u32x4){pk(s[kt][8 * j2 + 0], s[kt][8 * j2 + 1]), pk(s[kt][8 * j2 + 2], s[kt][8 * j2 + 3]), pk(s[kt][8 * j2 + 4], s[kt][8 * j2 + 5]), pk(s[kt][8 * j2 + 6], s[kt][8 * j2 + 7])};
;     XLAS float* wsf = (XLAS float*)(lds + X_WSF) + wid * 64;
;     if (hi == 0) wsf[r32] = l;
	v_sub_f32_e32 v24, v24, v128
	v_add_f32_e32 v60, v20, v60
	v_exp_f32_e32 v24, v24
	v_sub_f32_e32 v25, v25, v128
	v_add_f32_e32 v60, v21, v60
	v_exp_f32_e32 v25, v25
	v_sub_f32_e32 v26, v26, v128
	v_add_f32_e32 v60, v22, v60
	v_exp_f32_e32 v26, v26
	v_sub_f32_e32 v27, v27, v128
	v_add_f32_e32 v60, v23, v60
	v_exp_f32_e32 v27, v27
	v_sub_f32_e32 v28, v28, v128
	v_add_f32_e32 v60, v24, v60
	v_exp_f32_e32 v28, v28
	v_sub_f32_e32 v29, v29, v128
	v_add_f32_e32 v60, v25, v60
	v_exp_f32_e32 v29, v29
	v_sub_f32_e32 v30, v30, v128
	v_add_f32_e32 v60, v26, v60
	v_exp_f32_e32 v30, v30
	v_sub_f32_e32 v31, v31, v128
	v_add_f32_e32 v60, v27, v60
	v_exp_f32_e32 v31, v31
	v_sub_f32_e32 v0, v0, v128
	v_add_f32_e32 v60, v28, v60
	v_exp_f32_e32 v163, v0
	v_sub_f32_e32 v0, v1, v128
	v_add_f32_e32 v60, v29, v60
	v_exp_f32_e32 v164, v0
	v_sub_f32_e32 v0, v2, v128
	v_add_f32_e32 v60, v30, v60
	v_exp_f32_e32 v2, v0
	v_sub_f32_e32 v0, v3, v128
	v_add_f32_e32 v60, v31, v60
	v_exp_f32_e32 v3, v0
	v_sub_f32_e32 v1, v4, v128
	v_add_f32_e32 v0, v163, v60
	v_exp_f32_e32 v4, v1
	v_sub_f32_e32 v1, v5, v128
	v_add_f32_e32 v0, v164, v0
	v_exp_f32_e32 v5, v1
	v_sub_f32_e32 v1, v6, v128
	v_add_f32_e32 v0, v2, v0
	v_exp_f32_e32 v6, v1
	v_sub_f32_e32 v1, v7, v128
	v_add_f32_e32 v0, v3, v0
	v_exp_f32_e32 v7, v1
	v_sub_f32_e32 v1, v8, v128
	v_add_f32_e32 v0, v4, v0
	v_exp_f32_e32 v8, v1
	v_sub_f32_e32 v1, v9, v128
	v_add_f32_e32 v0, v5, v0
	v_exp_f32_e32 v9, v1
	v_sub_f32_e32 v1, v10, v128
	v_add_f32_e32 v0, v6, v0
	v_exp_f32_e32 v10, v1
	v_sub_f32_e32 v1, v11, v128
	v_add_f32_e32 v0, v7, v0
	v_exp_f32_e32 v11, v1
	v_sub_f32_e32 v1, v12, v128
	v_add_f32_e32 v0, v8, v0
	v_exp_f32_e32 v12, v1
	v_sub_f32_e32 v1, v13, v128
	v_add_f32_e32 v0, v9, v0
	v_exp_f32_e32 v13, v1
	v_sub_f32_e32 v1, v14, v128
	v_add_f32_e32 v0, v10, v0
	v_exp_f32_e32 v14, v1
	v_sub_f32_e32 v1, v15, v128
	v_add_f32_e32 v0, v11, v0
	v_exp_f32_e32 v15, v1
	v_add_f32_e32 v0, v12, v0
	v_add_f32_e32 v0, v13, v0
	v_add_f32_e32 v0, v14, v0
	v_add_f32_e32 v0, v15, v0
	ds_bpermute_b32 v1, v188, v0
	v_cvt_pk_bf16_f32 v92, v112, v113
	v_cvt_pk_bf16_f32 v93, v114, v115
	v_cvt_pk_bf16_f32 v94, v116, v117
	v_cvt_pk_bf16_f32 v95, v118, v119
	v_cvt_pk_bf16_f32 v88, v120, v121
	v_cvt_pk_bf16_f32 v89, v122, v123
	v_cvt_pk_bf16_f32 v90, v124, v125
	v_cvt_pk_bf16_f32 v91, v126, v127
	v_cvt_pk_bf16_f32 v84, v96, v97
	v_cvt_pk_bf16_f32 v85, v98, v99
	v_cvt_pk_bf16_f32 v86, v100, v101
	v_cvt_pk_bf16_f32 v87, v102, v103
	v_cvt_pk_bf16_f32 v80, v104, v105
	v_cvt_pk_bf16_f32 v81, v106, v107
	v_cvt_pk_bf16_f32 v82, v108, v109
	v_cvt_pk_bf16_f32 v83, v110, v111
	v_cvt_pk_bf16_f32 v76, v130, v131
	v_cvt_pk_bf16_f32 v77, v132, v133
	v_cvt_pk_bf16_f32 v78, v129, v134
	v_cvt_pk_bf16_f32 v79, v135, v136
	v_cvt_pk_bf16_f32 v72, v137, v138
	v_cvt_pk_bf16_f32 v73, v139, v140
	v_cvt_pk_bf16_f32 v74, v141, v142
	v_cvt_pk_bf16_f32 v75, v143, v147
	v_cvt_pk_bf16_f32 v68, v64, v65
	v_cvt_pk_bf16_f32 v69, v66, v67
	v_cvt_pk_bf16_f32 v70, v148, v149
	v_cvt_pk_bf16_f32 v71, v150, v71
	v_cvt_pk_bf16_f32 v64, v151, v152
	v_cvt_pk_bf16_f32 v65, v153, v154
	v_cvt_pk_bf16_f32 v66, v155, v156
	v_cvt_pk_bf16_f32 v67, v157, v158
	v_cvt_pk_bf16_f32 v60, v48, v49
	v_cvt_pk_bf16_f32 v61, v50, v51
	v_cvt_pk_bf16_f32 v62, v52, v53
	v_cvt_pk_bf16_f32 v63, v54, v55
	v_cvt_pk_bf16_f32 v56, v56, v57
	v_cvt_pk_bf16_f32 v57, v58, v59
	v_cvt_pk_bf16_f32 v58, v159, v160
	v_cvt_pk_bf16_f32 v59, v161, v162
	v_cvt_pk_bf16_f32 v52, v32, v33
	v_cvt_pk_bf16_f32 v53, v34, v35
	v_cvt_pk_bf16_f32 v54, v36, v37
	v_cvt_pk_bf16_f32 v55, v38, v39
	v_cvt_pk_bf16_f32 v48, v40, v41
	v_cvt_pk_bf16_f32 v49, v42, v43
	v_cvt_pk_bf16_f32 v50, v44, v45
	v_cvt_pk_bf16_f32 v51, v46, v47
	v_cvt_pk_bf16_f32 v44, v16, v17
	v_cvt_pk_bf16_f32 v45, v18, v19
	v_cvt_pk_bf16_f32 v46, v20, v21
	v_cvt_pk_bf16_f32 v47, v22, v23
	v_cvt_pk_bf16_f32 v40, v24, v25
	v_cvt_pk_bf16_f32 v41, v26, v27
	v_cvt_pk_bf16_f32 v42, v28, v29
	v_cvt_pk_bf16_f32 v43, v30, v31
	v_cvt_pk_bf16_f32 v36, v163, v164
	v_cvt_pk_bf16_f32 v37, v2, v3
	v_cvt_pk_bf16_f32 v38, v4, v5
	v_cvt_pk_bf16_f32 v39, v6, v7
	v_cvt_pk_bf16_f32 v32, v8, v9
	v_cvt_pk_bf16_f32 v33, v10, v11
	v_cvt_pk_bf16_f32 v34, v12, v13
	v_cvt_pk_bf16_f32 v35, v14, v15
	s_and_saveexec_b64 s[14:15], vcc
	s_cbranch_execz .LBB0_1144
	v_lshl_add_u32 v2, v191, 2, s17
	s_waitcnt lgkmcnt(0)
	v_add_f32_e32 v0, v0, v1
	ds_write_b32 v2, v0
	s_branch .LBB0_1144
